# P10 packed tiles with five queries x 6 heads per 32-row tile (30 rows used), tile pair of a task interleaved, static heavy+light unit pairing
# speedup vs baseline: 1.1492x; 1.0148x over previous
.LBB0_1257:
	s_cmp_lt_i32 s74, 11
	s_cselect_b64 s[2:3], -1, 0
	s_and_b64 s[16:17], s[2:3], s[0:1]
	s_andn2_b64 vcc, exec, s[16:17]
	s_cbranch_vccnz .LBB0_1495
	v_readlane_b32 s0, v254, 23
	v_lshlrev_b32_e32 v223, 2, v199
	v_readlane_b32 s6, v254, 29
	v_readlane_b32 s7, v254, 30
	v_readlane_b32 s12, v254, 35
	v_readlane_b32 s13, v254, 36
	s_nop 2
	global_load_dword v1, v223, s[6:7]
	s_nop 0
	global_load_dword v2, v223, s[12:13] offset:256
	s_waitcnt lgkmcnt(0)
	v_mbcnt_lo_u32_b32 v3, -1, 0
	v_mbcnt_hi_u32_b32 v3, -1, v3
	v_and_b32_e32 v4, 64, v3
	v_xor_b32_e32 v5, 1, v3
	v_add_u32_e32 v4, 64, v4
	v_cmp_lt_i32_e32 vcc, v5, v4
	v_xor_b32_e32 v6, 2, v3
	v_xor_b32_e32 v7, 4, v3
	v_cndmask_b32_e32 v5, v3, v5, vcc
	v_lshlrev_b32_e32 v5, 2, v5
	v_cmp_lt_i32_e32 vcc, v6, v4
	v_xor_b32_e32 v8, 8, v3
	v_xor_b32_e32 v9, 16, v3
	v_cndmask_b32_e32 v6, v3, v6, vcc
	v_lshlrev_b32_e32 v6, 2, v6
	v_cmp_lt_i32_e32 vcc, v7, v4
	v_xor_b32_e32 v10, 32, v3
	v_readlane_b32 s1, v254, 24
	v_cndmask_b32_e32 v7, v3, v7, vcc
	v_lshlrev_b32_e32 v7, 2, v7
	v_cmp_lt_i32_e32 vcc, v8, v4
	s_cmpk_eq_i32 s33, 0x100
	s_mov_b64 s[0:1], -1
	v_readlane_b32 s2, v254, 25
	v_readlane_b32 s3, v254, 26
	v_readlane_b32 s4, v254, 27
	v_readlane_b32 s5, v254, 28
	v_readlane_b32 s8, v254, 31
	v_readlane_b32 s9, v254, 32
	v_readlane_b32 s10, v254, 33
	v_readlane_b32 s11, v254, 34
	v_readlane_b32 s14, v254, 37
	v_readlane_b32 s15, v254, 38
	s_waitcnt vmcnt(0)
	v_and_b32_e32 v11, 0x7fffffff, v1
	v_and_b32_e32 v12, 0x7fffffff, v2
	ds_bpermute_b32 v11, v5, v11
	ds_bpermute_b32 v5, v5, v12
	v_max_f32_e64 v1, |v1|, |v1|
	v_max_f32_e64 v2, |v2|, |v2|
	s_waitcnt lgkmcnt(1)
	v_max_f32_e32 v11, v11, v11
	s_waitcnt lgkmcnt(0)
	v_max_f32_e32 v5, v5, v5
	v_max_f32_e32 v1, v1, v11
	v_max_f32_e32 v2, v2, v5
	ds_bpermute_b32 v5, v6, v1
	ds_bpermute_b32 v6, v6, v2
	s_waitcnt lgkmcnt(1)
	v_max_f32_e32 v5, v5, v5
	s_waitcnt lgkmcnt(0)
	v_max_f32_e32 v6, v6, v6
	v_max_f32_e32 v1, v1, v5
	v_max_f32_e32 v2, v2, v6
	ds_bpermute_b32 v5, v7, v1
	ds_bpermute_b32 v6, v7, v2
	v_cndmask_b32_e32 v7, v3, v8, vcc
	v_lshlrev_b32_e32 v7, 2, v7
	v_cmp_lt_i32_e32 vcc, v9, v4
	s_waitcnt lgkmcnt(1)
	v_max_f32_e32 v5, v5, v5
	s_waitcnt lgkmcnt(0)
	v_max_f32_e32 v6, v6, v6
	v_max_f32_e32 v1, v1, v5
	v_max_f32_e32 v2, v2, v6
	ds_bpermute_b32 v5, v7, v1
	ds_bpermute_b32 v6, v7, v2
	v_cndmask_b32_e32 v7, v3, v9, vcc
	v_lshlrev_b32_e32 v7, 2, v7
	v_cmp_lt_i32_e32 vcc, v10, v4
	s_waitcnt lgkmcnt(1)
	v_max_f32_e32 v5, v5, v5
	s_waitcnt lgkmcnt(0)
	v_max_f32_e32 v6, v6, v6
	v_max_f32_e32 v1, v1, v5
	v_max_f32_e32 v2, v2, v6
	ds_bpermute_b32 v5, v7, v1
	ds_bpermute_b32 v6, v7, v2
	v_cndmask_b32_e32 v3, v3, v10, vcc
	v_lshlrev_b32_e32 v205, 2, v3
	s_waitcnt lgkmcnt(1)
	v_max_f32_e32 v3, v5, v5
	s_waitcnt lgkmcnt(0)
	v_max_f32_e32 v4, v6, v6
	v_max_f32_e32 v1, v1, v3
	v_max_f32_e32 v2, v2, v4
	ds_bpermute_b32 v3, v205, v1
	ds_bpermute_b32 v4, v205, v2
	s_waitcnt lgkmcnt(1)
	v_max_f32_e32 v3, v3, v3
	s_waitcnt lgkmcnt(0)
	v_max_f32_e32 v4, v4, v4
	v_max_f32_e32 v1, v1, v3
	v_max_f32_e32 v2, v2, v4
	v_mul_f32_e32 v1, 0x4138aa3b, v1
	v_mul_f32_e32 v1, v1, v2
	v_mul_f32_e32 v222, 0x3f828f5c, v1
	s_cmpk_gt_i32 s80, 0x1ff
	s_cbranch_scc1 .LBB0_1340
	s_and_b32 s0, s77, 0x3fffffc
	s_lshl_b32 s34, s77, 3
	s_add_i32 s35, s0, 0
	s_add_u32 s36, s72, 0x8800000
	s_addc_u32 s37, s73, 0
	s_lshl_b32 s8, s77, 12
	s_add_u32 s20, s72, 0x9400000
	s_addc_u32 s21, s73, 0
	s_add_u32 s40, s72, 0x8400000
	s_addc_u32 s41, s73, 0
	s_lshl_b32 s0, s77, 9
	v_and_b32_e32 v1, 31, v198
	s_add_i32 s42, s0, 0
	s_and_b32 s43, s34, 24
	v_mul_u32_u24_e32 v3, 43, v1
	s_add_u32 s22, s72, 0xb400004
	v_lshrrev_b32_e32 v8, 8, v3
	s_addc_u32 s23, s73, 0
	v_lshrrev_b32_e32 v2, 5, v199
	v_mad_i32_i24 v3, v8, -6, v1
	v_cmp_gt_u32_e64 s[6:7], 24, v1
	s_add_u32 s24, s72, 0xda00000
	v_lshlrev_b32_e32 v4, 3, v2
	v_cndmask_b32_e64 v1, 0, v8, s[6:7]
	v_cndmask_b32_e64 v200, 0, v3, s[6:7]
	v_mov_b32_e32 v3, 0
	v_lshlrev_b64 v[6:7], v199, -1
	v_or_b32_e32 v227, 64, v199
	v_or_b32_e32 v228, 0x80, v199
	v_or_b32_e32 v229, 0xc0, v199
	v_lshlrev_b32_e32 v206, 2, v2
	s_addc_u32 s25, s73, 0
	s_lshr_b32 s0, s76, 3
	v_lshlrev_b32_e32 v2, 4, v199
	v_lshl_add_u32 v5, v199, 4, 0
	v_lshlrev_b32_e32 v201, 2, v198
	v_cmp_eq_u32_e32 vcc, 1, v198
	v_or_b32_e32 v226, s34, v1
	v_not_b32_e32 v1, v7
	v_not_b32_e32 v202, v6
	v_lshlrev_b32_e32 v9, 3, v227
	v_lshlrev_b32_e32 v10, 3, v228
	v_lshlrev_b32_e32 v11, 3, v229
	s_and_b32 s46, s0, 24
	v_lshl_add_u64 v[6:7], s[72:73], 0, v[2:3]
	s_mov_b64 s[0:1], 0xba00000
	v_mov_b32_e32 v212, -1
	s_mov_b32 s19, 0
	v_add_u32_e32 v203, 0, v201
	v_cmp_gt_u32_e64 s[2:3], 3, v198
	v_cndmask_b32_e64 v207, 0, -1, vcc
	v_cmp_eq_u32_e64 s[4:5], 0, v199
	v_or_b32_e32 v224, 2, v223
	v_or_b32_e32 v225, 3, v223
	v_lshlrev_b32_e32 v204, 3, v199
	v_lshlrev_b32_e64 v230, v8, 1
	v_lshlrev_b32_e64 v231, v8, 16
	v_lshl_add_u64 v[208:209], v[6:7], 0, s[0:1]
	s_mov_b64 s[26:27], 0x800
	s_movk_i32 s47, 0x600
	v_lshlrev_b32_e32 v210, 1, v4
	v_add_u32_e32 v232, s35, v9
	v_add_u32_e32 v233, s35, v10
	v_add_u32_e32 v234, s35, v11
	s_movk_i32 s48, 0x1000
	s_mov_b64 s[28:29], 0x1000
	s_movk_i32 s49, 0x90
	s_movk_i32 s50, 0x300
	v_mov_b32_e32 v213, v212
	v_add_u32_e32 v235, s8, v5
	v_mov_b32_e32 v236, 0x7149f2ca
	s_mov_b32 s96, 0
	s_branch .Lp10_pull

.Lp10_pull:
	s_cmp_ge_u32 s96, 2
	s_cbranch_scc1 .LBB0_1340
	s_lshr_b32 s12, s80, 1
	s_sub_i32 s13, 0xff, s12
	s_cmp_eq_u32 s96, 0
	s_cselect_b32 s12, s12, s13
	s_add_i32 s96, s96, 1
	s_lshl_b32 s12, s12, 1
	s_and_b32 s13, s80, 1
	s_sub_i32 s12, s12, s13
	s_add_i32 s12, s12, 1

.LBB0_1317:
	v_ashrrev_i32_e32 v219, 31, v218
	v_ashrrev_i32_e32 v215, 31, v214
	s_lshl_b32 s1, s10, 21
	s_add_u32 s8, s36, s1
	s_addc_u32 s9, s37, 0
	s_add_u32 s11, s40, s1
	s_addc_u32 s12, s41, 0
	s_movk_i32 s82, 0x660
	s_waitcnt vmcnt(0)
	v_lshlrev_b32_e32 v2, 4, v199
	v_mov_b32_e32 v22, v218
	v_and_b32_e32 v24, 31, v199
	v_mul_u32_u24_e32 v25, 43, v24
	v_lshrrev_b32_e32 v25, 8, v25
	v_mad_i32_i24 v24, v25, -6, v24
	v_and_b32_e32 v28, 31, v199
	v_cmp_gt_u32_e64 s[94:95], 30, v28
	v_lshlrev_b32_e64 v23, v25, 1
	v_cndmask_b32_e64 v25, 0, v25, s[94:95]
	v_mul_u32_u24_e32 v18, 6, v25
	v_mov_b32_e32 v19, 0x110
	v_mul_u32_u24_e32 v19, v19, v24
	v_lshl_add_u32 v19, v206, 2, v19
	v_add_u32_e32 v19, 0x4000, v19
	s_mul_i32 s0, s10, 6
	v_add_u32_e32 v20, s0, v24
	v_lshl_add_u32 v20, v20, 7, v210
	v_mov_b32_e32 v31, 0x110
	v_mul_u32_u24_e32 v31, v31, v24
	v_add_u32_e32 v31, 0x4100, v31
	v_add_u32_e32 v31, v31, v206
	v_mov_b32_e32 v82, 0
	v_mov_b32_e32 v83, 0
	v_mov_b32_e32 v84, 0
	v_mov_b32_e32 v85, 0
	s_lshl_b32 s0, s77, 10
	s_add_i32 s0, s0, 0x4000
	v_add_u32_e32 v28, s0, v2
	v_add_u32_e32 v29, 0x10000, v28
	ds_write_b128 v28, v[82:85]
	ds_write_b128 v28, v[82:85] offset:8192
	ds_write_b128 v28, v[82:85] offset:16384
	ds_write_b128 v28, v[82:85] offset:24576
	ds_write_b128 v28, v[82:85] offset:32768
	ds_write_b128 v28, v[82:85] offset:40960
	ds_write_b128 v28, v[82:85] offset:49152
	ds_write_b128 v28, v[82:85] offset:57344
	ds_write_b128 v29, v[82:85]
	ds_write_b128 v29, v[82:85] offset:8192
	ds_write_b128 v29, v[82:85] offset:16384
	ds_write_b128 v29, v[82:85] offset:24576
	ds_write_b128 v29, v[82:85] offset:32768
	v_mov_b32_e32 v86, 0x1800
	ds_write_b32 v86, v82
	ds_write_b64 v86, v[82:83] offset:8
	s_lshl_b32 s90, s77, 8
	s_add_i32 s90, s90, 0x1e000
	v_lshl_add_u32 v122, v199, 2, s90
	ds_write_b32 v122, v82
	s_waitcnt lgkmcnt(0)
	s_barrier
	v_and_b32_e32 v102, 31, v199
	s_lshl_b32 s0, s77, 5
	v_add_u32_e32 v103, s0, v102
	s_mov_b64 s[58:59], exec
	v_cmp_gt_u32_e32 vcc, 32, v199
	s_and_b64 exec, exec, vcc
	v_lshlrev_b32_e32 v106, 3, v103
	ds_read_b64 v[104:105], v106
	s_waitcnt lgkmcnt(0)
	v_bcnt_u32_b32 v107, v104, 0
	v_bcnt_u32_b32 v107, v105, v107
	v_add_u32_e32 v108, 4, v107
	v_mul_u32_u24_e32 v108, 0xcd, v108
	v_lshrrev_b32_e32 v108, 10, v108
	v_cmp_eq_u32_e64 s[92:93], 64, v107
	v_cndmask_b32_e64 v107, v107, 0, s[92:93]
	v_mov_b32_e32 v110, 0x1800
	ds_add_rtn_u32 v109, v110, v108
	s_waitcnt lgkmcnt(0)
.Lq_build:
	v_cmp_ne_u32_e32 vcc, 0, v107
	s_and_b64 exec, exec, vcc
	s_cbranch_execz .Lq_build_done
	v_mov_b32_e32 v118, 0
	v_mov_b32_e32 v119, 0
	v_ffbl_b32_e32 v111, v104
	v_ffbl_b32_e32 v112, v105
	v_add_u32_e32 v112, 32, v112
	v_cmp_ne_u32_e32 vcc, 0, v104
	v_cndmask_b32_e32 v111, v112, v111, vcc
	v_cmp_ne_u32_e64 s[14:15], 0, v107
	v_lshlrev_b32_e64 v113, v111, 1
	v_not_b32_e32 v113, v113
	v_cndmask_b32_e32 v114, -1, v113, vcc
	v_cndmask_b32_e64 v115, v113, -1, vcc
	v_and_b32_e32 v104, v104, v114
	v_and_b32_e32 v105, v105, v115
	v_lshlrev_b32_e32 v116, 0, v111
	v_cndmask_b32_e64 v116, 0, v116, s[14:15]
	v_or_b32_e32 v118, v118, v116
	v_cndmask_b32_e64 v117, 0, 1, s[14:15]
	v_add_u32_e32 v119, v119, v117
	v_sub_u32_e32 v107, v107, v117
	v_ffbl_b32_e32 v111, v104
	v_ffbl_b32_e32 v112, v105
	v_add_u32_e32 v112, 32, v112
	v_cmp_ne_u32_e32 vcc, 0, v104
	v_cndmask_b32_e32 v111, v112, v111, vcc
	v_cmp_ne_u32_e64 s[14:15], 0, v107
	v_lshlrev_b32_e64 v113, v111, 1
	v_not_b32_e32 v113, v113
	v_cndmask_b32_e32 v114, -1, v113, vcc
	v_cndmask_b32_e64 v115, v113, -1, vcc
	v_and_b32_e32 v104, v104, v114
	v_and_b32_e32 v105, v105, v115
	v_lshlrev_b32_e32 v116, 6, v111
	v_cndmask_b32_e64 v116, 0, v116, s[14:15]
	v_or_b32_e32 v118, v118, v116
	v_cndmask_b32_e64 v117, 0, 1, s[14:15]
	v_add_u32_e32 v119, v119, v117
	v_sub_u32_e32 v107, v107, v117
	v_ffbl_b32_e32 v111, v104
	v_ffbl_b32_e32 v112, v105
	v_add_u32_e32 v112, 32, v112
	v_cmp_ne_u32_e32 vcc, 0, v104
	v_cndmask_b32_e32 v111, v112, v111, vcc
	v_cmp_ne_u32_e64 s[14:15], 0, v107
	v_lshlrev_b32_e64 v113, v111, 1
	v_not_b32_e32 v113, v113
	v_cndmask_b32_e32 v114, -1, v113, vcc
	v_cndmask_b32_e64 v115, v113, -1, vcc
	v_and_b32_e32 v104, v104, v114
	v_and_b32_e32 v105, v105, v115
	v_lshlrev_b32_e32 v116, 12, v111
	v_cndmask_b32_e64 v116, 0, v116, s[14:15]
	v_or_b32_e32 v118, v118, v116
	v_cndmask_b32_e64 v117, 0, 1, s[14:15]
	v_add_u32_e32 v119, v119, v117
	v_sub_u32_e32 v107, v107, v117
	v_ffbl_b32_e32 v111, v104
	v_ffbl_b32_e32 v112, v105
	v_add_u32_e32 v112, 32, v112
	v_cmp_ne_u32_e32 vcc, 0, v104
	v_cndmask_b32_e32 v111, v112, v111, vcc
	v_cmp_ne_u32_e64 s[14:15], 0, v107
	v_lshlrev_b32_e64 v113, v111, 1
	v_not_b32_e32 v113, v113
	v_cndmask_b32_e32 v114, -1, v113, vcc
	v_cndmask_b32_e64 v115, v113, -1, vcc
	v_and_b32_e32 v104, v104, v114
	v_and_b32_e32 v105, v105, v115
	v_lshlrev_b32_e32 v116, 18, v111
	v_cndmask_b32_e64 v116, 0, v116, s[14:15]
	v_or_b32_e32 v118, v118, v116
	v_cndmask_b32_e64 v117, 0, 1, s[14:15]
	v_add_u32_e32 v119, v119, v117
	v_sub_u32_e32 v107, v107, v117
	v_ffbl_b32_e32 v111, v104
	v_ffbl_b32_e32 v112, v105
	v_add_u32_e32 v112, 32, v112
	v_cmp_ne_u32_e32 vcc, 0, v104
	v_cndmask_b32_e32 v111, v112, v111, vcc
	v_cmp_ne_u32_e64 s[14:15], 0, v107
	v_lshlrev_b32_e64 v113, v111, 1
	v_not_b32_e32 v113, v113
	v_cndmask_b32_e32 v114, -1, v113, vcc
	v_cndmask_b32_e64 v115, v113, -1, vcc
	v_and_b32_e32 v104, v104, v114
	v_and_b32_e32 v105, v105, v115
	v_lshlrev_b32_e32 v116, 24, v111
	v_cndmask_b32_e64 v116, 0, v116, s[14:15]
	v_or_b32_e32 v118, v118, v116
	v_cndmask_b32_e64 v117, 0, 1, s[14:15]
	v_add_u32_e32 v119, v119, v117
	v_sub_u32_e32 v107, v107, v117
	v_lshl_or_b32 v120, v119, 8, v103
	v_mov_b32_e32 v121, v118
	v_lshlrev_b32_e32 v122, 3, v109
	ds_write_b64 v122, v[120:121] offset:2048
	v_add_u32_e32 v109, 1, v109
	s_branch .Lq_build

.Lq_full:
	s_cmp_eq_u64 s[92:93], 0
	s_cbranch_scc1 .Lq_full_done
	s_ff1_i32_b64 s0, s[92:93]
	s_bitset0_b64 s[92:93], s0
	s_nop 3
	v_readlane_b32 s1, v103, s0
	v_readlane_b32 s14, v109, s0
	v_cmp_eq_u32_e32 vcc, 12, v199
	v_cndmask_b32_e64 v120, 5, 4, vcc
	v_lshl_or_b32 v120, v120, 8, s1
	v_mul_u32_u24_e32 v121, 5, v199
	v_mov_b32_e32 v123, 0x1041041
	v_mul_lo_u32 v121, v121, v123
	v_add_u32_e32 v121, 0x40c2040, v121
	v_add_lshl_u32 v122, v199, s14, 3
	v_cmp_gt_u32_e32 vcc, 13, v199
	s_and_b64 exec, exec, vcc
	ds_write_b64 v122, v[120:121] offset:2048
	s_mov_b64 exec, s[58:59]
	s_branch .Lq_full

.Lq_again:
	s_mov_b32 s52, 0
	s_mov_b32 s69, 0
	s_min_u32 s14, s69, 63
	s_nop 3
	v_readlane_b32 s30, v33, s14
	s_and_b32 s30, s30, 0xff
	s_lshl_b32 s30, s30, 13
	s_add_u32 s64, s11, s30
	s_addc_u32 s65, s12, 0
	s_add_u32 s66, s8, s30
	s_addc_u32 s67, s9, 0
	global_load_dwordx4 v[178:181], v2, s[64:65]
	global_load_dwordx4 v[174:177], v2, s[64:65] offset:1024
	global_load_dwordx4 v[170:173], v2, s[64:65] offset:2048
	global_load_dwordx4 v[166:169], v2, s[64:65] offset:3072
	global_load_dwordx4 v[146:149], v2, s[66:67]
	global_load_dwordx4 v[142:145], v2, s[66:67] offset:1024
	global_load_dwordx4 v[126:129], v2, s[66:67] offset:2048
	global_load_dwordx4 v[114:117], v2, s[66:67] offset:3072
	s_mov_b32 s69, 0
	s_min_u32 s14, s69, 63
	s_nop 3
	v_readlane_b32 s30, v26, s14
	v_readlane_b32 s31, v27, s14
	v_bfe_u32 v28, s31, v18, 6
	v_lshl_add_u32 v29, s99, 6, v28
	v_mad_u32_u24 v29, v29, s47, v20
	global_load_dwordx4 v[238:241], v29, s[20:21]
	global_load_dwordx4 v[242:245], v29, s[20:21] offset:32
	global_load_dwordx4 v[246:249], v29, s[20:21] offset:64
	global_load_dwordx4 v[250:253], v29, s[20:21] offset:96
	s_mov_b32 s69, 0
	s_min_u32 s14, s69, 63
	s_nop 3
	v_readlane_b32 s30, v33, s14
	s_and_b32 s30, s30, 0xff
	s_lshl_b32 s30, s30, 13
	s_or_b32 s30, s30, 0x1000
	s_add_u32 s64, s11, s30
	s_addc_u32 s65, s12, 0
	s_add_u32 s66, s8, s30
	s_addc_u32 s67, s9, 0
	global_load_dwordx4 v[162:165], v2, s[64:65]
	global_load_dwordx4 v[154:157], v2, s[64:65] offset:1024
	global_load_dwordx4 v[150:153], v2, s[64:65] offset:2048
	global_load_dwordx4 v[158:161], v2, s[64:65] offset:3072
	global_load_dwordx4 v[138:141], v2, s[66:67]
	global_load_dwordx4 v[122:125], v2, s[66:67] offset:1024
	global_load_dwordx4 v[110:113], v2, s[66:67] offset:2048
	global_load_dwordx4 v[106:109], v2, s[66:67] offset:3072
	s_mov_b32 s69, 1
	s_min_u32 s14, s69, 63
	s_nop 3
	v_readlane_b32 s30, v33, s14
	s_and_b32 s30, s30, 0xff
	s_lshl_b32 s30, s30, 13
	s_add_u32 s64, s11, s30
	s_addc_u32 s65, s12, 0
	s_add_u32 s66, s8, s30
	s_addc_u32 s67, s9, 0
	global_load_dwordx4 v[194:197], v2, s[64:65]
	global_load_dwordx4 v[190:193], v2, s[64:65] offset:1024
	global_load_dwordx4 v[186:189], v2, s[64:65] offset:2048
	global_load_dwordx4 v[182:185], v2, s[64:65] offset:3072
	global_load_dwordx4 v[134:137], v2, s[66:67]
	global_load_dwordx4 v[130:133], v2, s[66:67] offset:1024
	global_load_dwordx4 v[118:121], v2, s[66:67] offset:2048
	global_load_dwordx4 v[102:105], v2, s[66:67] offset:3072

.Lq_wd_k0:
	v_mov_b32_e32 v4, v238
	v_mov_b32_e32 v5, v239
	v_mov_b32_e32 v6, v240
	v_mov_b32_e32 v7, v241
	v_mov_b32_e32 v8, v242
	v_mov_b32_e32 v9, v243
	v_mov_b32_e32 v10, v244
	v_mov_b32_e32 v11, v245
	v_mov_b32_e32 v12, v246
	v_mov_b32_e32 v13, v247
	v_mov_b32_e32 v14, v248
	v_mov_b32_e32 v15, v249
	v_mov_b32_e32 v98, v250
	v_mov_b32_e32 v99, v251
	v_mov_b32_e32 v100, v252
	v_mov_b32_e32 v101, v253
	v_bfe_u32 v28, s57, v18, 6
	v_lshl_add_u32 v218, s99, 6, v28
	v_mad_u32_u24 v21, v28, s82, v19
	v_mad_u32_u24 v32, v28, s82, v31
	v_and_b32_e32 v29, s18, v23
	v_cmp_ne_u32_e64 s[54:55], 0, v29
	s_and_b64 s[54:55], s[54:55], s[94:95]
	s_min_u32 s14, s85, 63
	s_nop 3
	v_readlane_b32 s30, v26, s14
	v_readlane_b32 s31, v27, s14
	v_bfe_u32 v28, s31, v18, 6
	v_lshl_add_u32 v29, s99, 6, v28
	v_mad_u32_u24 v29, v29, s47, v20
	global_load_dwordx4 v[238:241], v29, s[20:21]
	global_load_dwordx4 v[242:245], v29, s[20:21] offset:32
	global_load_dwordx4 v[246:249], v29, s[20:21] offset:64
	global_load_dwordx4 v[250:253], v29, s[20:21] offset:96
	s_lshl_b32 s0, s100, 6
	v_or_b32_e32 v237, s0, v206
	v_mov_b32_e32 v221, 0
	s_cmp_lg_u32 s100, s99
	s_cbranch_scc1 .Lq_s0n_k0
	v_and_b32_e32 v82, s18, v23
	v_cmp_ne_u32_e32 vcc, 0, v82
	s_and_b64 vcc, s[94:95], vcc
	v_mov_b32 v83, 0
	v_or_b32_e32 v16, 2, v237
	v_cndmask_b32_e32 v82, v236, v222, vcc
	v_sub_f32_e32 v82, v83, v82
	v_mov_b32_e32 v83, v82
	v_mov_b32_e32 v84, v82
	v_mov_b32_e32 v85, v82
	v_mov_b32_e32 v86, v82
	v_mov_b32_e32 v87, v82
	v_mov_b32_e32 v88, v82
	v_mov_b32_e32 v89, v82
	v_mov_b32_e32 v90, v82
	v_mov_b32_e32 v91, v82
	v_mov_b32_e32 v92, v82
	v_mov_b32_e32 v93, v82
	v_mov_b32_e32 v94, v82
	v_mov_b32_e32 v95, v82
	v_mov_b32_e32 v96, v82
	v_mov_b32_e32 v97, v82
	v_cmp_le_i32_e32 vcc, v237, v218
	v_or_b32_e32 v17, 3, v237
	v_mfma_f32_32x32x16_bf16 v[82:97], v[178:181], v[4:7], v[82:97]
	v_or_b32_e32 v30, 8, v237
	v_mfma_f32_32x32x16_bf16 v[82:97], v[174:177], v[8:11], v[82:97]
	v_mfma_f32_32x32x16_bf16 v[82:97], v[170:173], v[12:15], v[82:97]
	v_mfma_f32_32x32x16_bf16 v[82:97], v[166:169], v[98:101], v[82:97]
	s_nop 11
	v_exp_f32_e32 v82, v82
	v_exp_f32_e32 v83, v83
	v_exp_f32_e32 v84, v84
	v_exp_f32_e32 v85, v85
	v_exp_f32_e32 v86, v86
	v_cndmask_b32_e32 v82, 0, v82, vcc
	v_cmp_lt_i32_e32 vcc, v237, v218
	v_exp_f32_e32 v87, v87
	v_exp_f32_e32 v88, v88
	v_cndmask_b32_e32 v83, 0, v83, vcc
	v_cmp_le_i32_e32 vcc, v16, v218
	v_or_b32_e32 v16, 9, v237
	v_exp_f32_e32 v89, v89
	v_cndmask_b32_e32 v84, 0, v84, vcc
	v_cmp_le_i32_e32 vcc, v17, v218
	v_exp_f32_e32 v90, v90
	v_exp_f32_e32 v91, v91
	v_cndmask_b32_e32 v85, 0, v85, vcc
	v_cmp_le_i32_e32 vcc, v30, v218
	v_add_f32_e32 v221, v221, v82
	v_exp_f32_e32 v92, v92
	v_cndmask_b32_e32 v86, 0, v86, vcc
	v_cmp_le_i32_e32 vcc, v16, v218
	v_or_b32_e32 v16, 10, v237
	v_add_f32_e32 v221, v83, v221
	v_cndmask_b32_e32 v87, 0, v87, vcc
	v_cmp_le_i32_e32 vcc, v16, v218
	v_or_b32_e32 v16, 11, v237
	v_exp_f32_e32 v93, v93
	v_cndmask_b32_e32 v88, 0, v88, vcc
	v_cmp_le_i32_e32 vcc, v16, v218
	v_or_b32_e32 v16, 16, v237
	v_add_f32_e32 v221, v84, v221
	v_cndmask_b32_e32 v89, 0, v89, vcc
	v_cmp_le_i32_e32 vcc, v16, v218
	v_or_b32_e32 v16, 17, v237
	v_exp_f32_e32 v94, v94
	v_cndmask_b32_e32 v90, 0, v90, vcc
	v_cmp_le_i32_e32 vcc, v16, v218
	v_or_b32_e32 v16, 18, v237
	v_add_f32_e32 v221, v85, v221
	v_cndmask_b32_e32 v91, 0, v91, vcc
	v_cmp_le_i32_e32 vcc, v16, v218
	v_or_b32_e32 v16, 19, v237
	v_exp_f32_e32 v95, v95
	v_add_f32_e32 v221, v86, v221
	v_cndmask_b32_e32 v92, 0, v92, vcc
	v_cmp_le_i32_e32 vcc, v16, v218
	v_or_b32_e32 v16, 24, v237
	v_cvt_pk_bf16_f32 v82, v82, v83
	v_cvt_pk_bf16_f32 v83, v84, v85
	v_cvt_pk_bf16_f32 v84, v86, v87
	v_cvt_pk_bf16_f32 v85, v88, v89
	v_add_f32_e32 v221, v87, v221
	v_cndmask_b32_e32 v93, 0, v93, vcc
	v_cmp_le_i32_e32 vcc, v16, v218
	v_or_b32_e32 v16, 25, v237
	v_mfma_f32_32x32x16_bf16 v[66:81], v[146:149], v[82:85], 0
	v_add_f32_e32 v221, v88, v221
	v_cndmask_b32_e32 v94, 0, v94, vcc
	v_exp_f32_e32 v86, v96
	v_cmp_le_i32_e32 vcc, v16, v218
	v_or_b32_e32 v88, 26, v237
	v_add_f32_e32 v221, v89, v221
	v_cndmask_b32_e32 v87, 0, v95, vcc
	v_mfma_f32_32x32x16_bf16 v[50:65], v[142:145], v[82:85], 0
	v_cmp_le_i32_e32 vcc, v88, v218
	v_exp_f32_e32 v88, v97
	v_or_b32_e32 v82, 27, v237
	v_cndmask_b32_e32 v86, 0, v86, vcc
	v_cmp_le_i32_e32 vcc, v82, v218
	v_cvt_pk_bf16_f32 v82, v90, v91
	v_cvt_pk_bf16_f32 v83, v92, v93
	v_cndmask_b32_e32 v88, 0, v88, vcc
	v_cvt_pk_bf16_f32 v84, v94, v87
	v_cvt_pk_bf16_f32 v85, v86, v88
	v_add_f32_e32 v221, v90, v221
	v_add_f32_e32 v89, v91, v221
	v_mfma_f32_32x32x16_bf16 v[66:81], v[126:129], v[82:85], v[66:81]
	v_add_f32_e32 v89, v92, v89
	v_add_f32_e32 v89, v93, v89
	v_add_f32_e32 v89, v94, v89
	v_add_f32_e32 v87, v87, v89
	v_add_f32_e32 v86, v86, v87
	v_add_f32_e32 v221, v88, v86
	v_mfma_f32_32x32x16_bf16 v[50:65], v[114:117], v[82:85], v[50:65]
	s_cmp_lg_u32 s85, s86
	s_cbranch_scc1 .Lq_nl0_k0
	s_min_u32 s14, s87, 63
	s_nop 3
	v_readlane_b32 s30, v33, s14
	s_and_b32 s30, s30, 0xff
	s_lshl_b32 s30, s30, 13
	s_or_b32 s30, s30, 0x1000
	s_add_u32 s64, s11, s30
	s_addc_u32 s65, s12, 0
	s_add_u32 s66, s8, s30
	s_addc_u32 s67, s9, 0
	global_load_dwordx4 v[178:181], v2, s[64:65]
	global_load_dwordx4 v[174:177], v2, s[64:65] offset:1024
	global_load_dwordx4 v[170:173], v2, s[64:65] offset:2048
	global_load_dwordx4 v[166:169], v2, s[64:65] offset:3072
	global_load_dwordx4 v[146:149], v2, s[66:67]
	global_load_dwordx4 v[142:145], v2, s[66:67] offset:1024
	global_load_dwordx4 v[126:129], v2, s[66:67] offset:2048
	global_load_dwordx4 v[114:117], v2, s[66:67] offset:3072
	s_waitcnt vmcnt(20)
	s_branch .Lq_nl0d_k0

.Lq_nl0d_k0:
	s_lshl_b32 s0, s100, 6
	s_or_b32 s0, s0, 32
	v_or_b32_e32 v237, s0, v206
	v_and_b32_e32 v82, s18, v23
	v_cmp_ne_u32_e32 vcc, 0, v82
	s_and_b64 vcc, s[94:95], vcc
	v_mov_b32 v83, 0
	v_or_b32_e32 v16, 2, v237
	v_cndmask_b32_e32 v82, v236, v222, vcc
	v_sub_f32_e32 v82, v83, v82
	v_mov_b32_e32 v83, v82
	v_mov_b32_e32 v84, v82
	v_mov_b32_e32 v85, v82
	v_mov_b32_e32 v86, v82
	v_mov_b32_e32 v87, v82
	v_mov_b32_e32 v88, v82
	v_mov_b32_e32 v89, v82
	v_mov_b32_e32 v90, v82
	v_mov_b32_e32 v91, v82
	v_mov_b32_e32 v92, v82
	v_mov_b32_e32 v93, v82
	v_mov_b32_e32 v94, v82
	v_mov_b32_e32 v95, v82
	v_mov_b32_e32 v96, v82
	v_mov_b32_e32 v97, v82
	v_cmp_le_i32_e32 vcc, v237, v218
	v_or_b32_e32 v17, 3, v237
	v_mfma_f32_32x32x16_bf16 v[82:97], v[162:165], v[4:7], v[82:97]
	v_or_b32_e32 v30, 8, v237
	v_mfma_f32_32x32x16_bf16 v[82:97], v[154:157], v[8:11], v[82:97]
	v_mfma_f32_32x32x16_bf16 v[82:97], v[150:153], v[12:15], v[82:97]
	v_mfma_f32_32x32x16_bf16 v[82:97], v[158:161], v[98:101], v[82:97]
	s_nop 11
	v_exp_f32_e32 v82, v82
	v_exp_f32_e32 v83, v83
	v_exp_f32_e32 v84, v84
	v_exp_f32_e32 v85, v85
	v_exp_f32_e32 v86, v86
	v_cndmask_b32_e32 v82, 0, v82, vcc
	v_cmp_lt_i32_e32 vcc, v237, v218
	v_exp_f32_e32 v87, v87
	v_exp_f32_e32 v88, v88
	v_cndmask_b32_e32 v83, 0, v83, vcc
	v_cmp_le_i32_e32 vcc, v16, v218
	v_or_b32_e32 v16, 9, v237
	v_exp_f32_e32 v89, v89
	v_cndmask_b32_e32 v84, 0, v84, vcc
	v_cmp_le_i32_e32 vcc, v17, v218
	v_exp_f32_e32 v90, v90
	v_exp_f32_e32 v91, v91
	v_cndmask_b32_e32 v85, 0, v85, vcc
	v_cmp_le_i32_e32 vcc, v30, v218
	v_add_f32_e32 v221, v221, v82
	v_exp_f32_e32 v92, v92
	v_cndmask_b32_e32 v86, 0, v86, vcc
	v_cmp_le_i32_e32 vcc, v16, v218
	v_or_b32_e32 v16, 10, v237
	v_add_f32_e32 v221, v83, v221
	v_cndmask_b32_e32 v87, 0, v87, vcc
	v_cmp_le_i32_e32 vcc, v16, v218
	v_or_b32_e32 v16, 11, v237
	v_exp_f32_e32 v93, v93
	v_cndmask_b32_e32 v88, 0, v88, vcc
	v_cmp_le_i32_e32 vcc, v16, v218
	v_or_b32_e32 v16, 16, v237
	v_add_f32_e32 v221, v84, v221
	v_cndmask_b32_e32 v89, 0, v89, vcc
	v_cmp_le_i32_e32 vcc, v16, v218
	v_or_b32_e32 v16, 17, v237
	v_exp_f32_e32 v94, v94
	v_cndmask_b32_e32 v90, 0, v90, vcc
	v_cmp_le_i32_e32 vcc, v16, v218
	v_or_b32_e32 v16, 18, v237
	v_add_f32_e32 v221, v85, v221
	v_cndmask_b32_e32 v91, 0, v91, vcc
	v_cmp_le_i32_e32 vcc, v16, v218
	v_or_b32_e32 v16, 19, v237
	v_exp_f32_e32 v95, v95
	v_add_f32_e32 v221, v86, v221
	v_cndmask_b32_e32 v92, 0, v92, vcc
	v_cmp_le_i32_e32 vcc, v16, v218
	v_or_b32_e32 v16, 24, v237
	v_cvt_pk_bf16_f32 v82, v82, v83
	v_cvt_pk_bf16_f32 v83, v84, v85
	v_cvt_pk_bf16_f32 v84, v86, v87
	v_cvt_pk_bf16_f32 v85, v88, v89
	v_add_f32_e32 v221, v87, v221
	v_cndmask_b32_e32 v93, 0, v93, vcc
	v_cmp_le_i32_e32 vcc, v16, v218
	v_or_b32_e32 v16, 25, v237
	v_mfma_f32_32x32x16_bf16 v[66:81], v[138:141], v[82:85], v[66:81]
	v_add_f32_e32 v221, v88, v221
	v_cndmask_b32_e32 v94, 0, v94, vcc
	v_exp_f32_e32 v86, v96
	v_cmp_le_i32_e32 vcc, v16, v218
	v_or_b32_e32 v88, 26, v237
	v_add_f32_e32 v221, v89, v221
	v_cndmask_b32_e32 v87, 0, v95, vcc
	v_mfma_f32_32x32x16_bf16 v[50:65], v[122:125], v[82:85], v[50:65]
	v_cmp_le_i32_e32 vcc, v88, v218
	v_exp_f32_e32 v88, v97
	v_or_b32_e32 v82, 27, v237
	v_cndmask_b32_e32 v86, 0, v86, vcc
	v_cmp_le_i32_e32 vcc, v82, v218
	v_cvt_pk_bf16_f32 v82, v90, v91
	v_cvt_pk_bf16_f32 v83, v92, v93
	v_cndmask_b32_e32 v88, 0, v88, vcc
	v_cvt_pk_bf16_f32 v84, v94, v87
	v_cvt_pk_bf16_f32 v85, v86, v88
	v_add_f32_e32 v221, v90, v221
	v_add_f32_e32 v89, v91, v221
	v_mfma_f32_32x32x16_bf16 v[66:81], v[110:113], v[82:85], v[66:81]
	v_add_f32_e32 v89, v92, v89
	v_add_f32_e32 v89, v93, v89
	v_add_f32_e32 v89, v94, v89
	v_add_f32_e32 v87, v87, v89
	v_add_f32_e32 v86, v86, v87
	v_add_f32_e32 v221, v88, v86
	v_mfma_f32_32x32x16_bf16 v[50:65], v[106:109], v[82:85], v[50:65]
	s_cmp_lg_u32 s85, s86
	s_cbranch_scc1 .Lq_nl1_k0
	s_min_u32 s14, s88, 63
	s_nop 3
	v_readlane_b32 s30, v33, s14
	s_and_b32 s30, s30, 0xff
	s_lshl_b32 s30, s30, 13
	s_add_u32 s64, s11, s30
	s_addc_u32 s65, s12, 0
	s_add_u32 s66, s8, s30
	s_addc_u32 s67, s9, 0
	global_load_dwordx4 v[162:165], v2, s[64:65]
	global_load_dwordx4 v[154:157], v2, s[64:65] offset:1024
	global_load_dwordx4 v[150:153], v2, s[64:65] offset:2048
	global_load_dwordx4 v[158:161], v2, s[64:65] offset:3072
	global_load_dwordx4 v[138:141], v2, s[66:67]
	global_load_dwordx4 v[122:125], v2, s[66:67] offset:1024
	global_load_dwordx4 v[110:113], v2, s[66:67] offset:2048
	global_load_dwordx4 v[106:109], v2, s[66:67] offset:3072
	s_branch .Lq_nl1_k0
.Lq_s0n_k0:
	v_and_b32_e32 v82, s18, v23
	v_cmp_ne_u32_e32 vcc, 0, v82
	s_and_b64 vcc, s[94:95], vcc
	v_mov_b32 v83, 0
	v_cndmask_b32_e32 v82, v236, v222, vcc
	v_sub_f32_e32 v82, v83, v82
	v_mov_b32_e32 v83, v82
	v_mov_b32_e32 v84, v82
	v_mov_b32_e32 v85, v82
	v_mov_b32_e32 v86, v82
	v_mov_b32_e32 v87, v82
	v_mov_b32_e32 v88, v82
	v_mov_b32_e32 v89, v82
	v_mov_b32_e32 v90, v82
	v_mov_b32_e32 v91, v82
	v_mov_b32_e32 v92, v82
	v_mov_b32_e32 v93, v82
	v_mov_b32_e32 v94, v82
	v_mov_b32_e32 v95, v82
	v_mov_b32_e32 v96, v82
	v_mov_b32_e32 v97, v82
	s_nop 1
	v_mfma_f32_32x32x16_bf16 v[82:97], v[178:181], v[4:7], v[82:97]
	v_mfma_f32_32x32x16_bf16 v[82:97], v[174:177], v[8:11], v[82:97]
	v_mfma_f32_32x32x16_bf16 v[82:97], v[170:173], v[12:15], v[82:97]
	v_mfma_f32_32x32x16_bf16 v[82:97], v[166:169], v[98:101], v[82:97]
	s_waitcnt vmcnt(12)
	v_mov_b32_e32 v28, 0
	v_and_b32_e32 v34, s18, v23
	v_cmp_ne_u32_e32 vcc, 0, v34
	s_and_b64 vcc, s[94:95], vcc
	v_mov_b32 v35, 0
	v_cndmask_b32_e32 v34, v236, v222, vcc
	v_sub_f32_e32 v34, v35, v34
	v_mov_b32_e32 v35, v34
	v_mov_b32_e32 v36, v34
	v_mov_b32_e32 v37, v34
	v_mov_b32_e32 v38, v34
	v_mov_b32_e32 v39, v34
	v_mov_b32_e32 v40, v34
	v_mov_b32_e32 v41, v34
	v_mov_b32_e32 v42, v34
	v_mov_b32_e32 v43, v34
	v_mov_b32_e32 v44, v34
	v_mov_b32_e32 v45, v34
	v_mov_b32_e32 v46, v34
	v_mov_b32_e32 v47, v34
	v_mov_b32_e32 v48, v34
	v_mov_b32_e32 v49, v34
	s_nop 1
	v_mfma_f32_32x32x16_bf16 v[34:49], v[162:165], v[4:7], v[34:49]
	v_mfma_f32_32x32x16_bf16 v[34:49], v[154:157], v[8:11], v[34:49]
	v_mfma_f32_32x32x16_bf16 v[34:49], v[150:153], v[12:15], v[34:49]
	v_mfma_f32_32x32x16_bf16 v[34:49], v[158:161], v[98:101], v[34:49]
	v_exp_f32_e32 v82, v82
	v_exp_f32_e32 v83, v83
	v_exp_f32_e32 v84, v84
	v_exp_f32_e32 v85, v85
	v_exp_f32_e32 v86, v86
	v_exp_f32_e32 v87, v87
	v_exp_f32_e32 v88, v88
	v_exp_f32_e32 v89, v89
	v_exp_f32_e32 v90, v90
	v_exp_f32_e32 v91, v91
	v_add_f32_e32 v221, v221, v82
	v_exp_f32_e32 v92, v92
	v_exp_f32_e32 v34, v34
	v_add_f32_e32 v221, v83, v221
	v_exp_f32_e32 v35, v35
	v_exp_f32_e32 v93, v93
	v_exp_f32_e32 v36, v36
	v_add_f32_e32 v221, v84, v221
	v_exp_f32_e32 v37, v37
	v_exp_f32_e32 v94, v94
	v_exp_f32_e32 v38, v38
	v_add_f32_e32 v221, v85, v221
	v_exp_f32_e32 v39, v39
	v_exp_f32_e32 v95, v95
	v_exp_f32_e32 v40, v40
	v_add_f32_e32 v221, v86, v221
	v_exp_f32_e32 v41, v41
	v_cvt_pk_bf16_f32 v82, v82, v83
	v_exp_f32_e32 v42, v42
	v_cvt_pk_bf16_f32 v83, v84, v85
	v_exp_f32_e32 v43, v43
	v_cvt_pk_bf16_f32 v84, v86, v87
	v_add_f32_e32 v28, v28, v34
	v_cvt_pk_bf16_f32 v85, v88, v89
	v_exp_f32_e32 v44, v44
	v_add_f32_e32 v221, v87, v221
	v_add_f32_e32 v28, v35, v28
	v_mfma_f32_32x32x16_bf16 v[66:81], v[146:149], v[82:85], 0
	v_exp_f32_e32 v45, v45
	v_add_f32_e32 v221, v88, v221
	v_add_f32_e32 v28, v36, v28
	v_exp_f32_e32 v86, v96
	v_exp_f32_e32 v46, v46
	v_add_f32_e32 v221, v89, v221
	v_add_f32_e32 v28, v37, v28
	v_mov_b32_e32 v87, v95
	v_exp_f32_e32 v47, v47
	v_mfma_f32_32x32x16_bf16 v[50:65], v[142:145], v[82:85], 0
	v_add_f32_e32 v28, v38, v28
	v_exp_f32_e32 v88, v97
	v_cvt_pk_bf16_f32 v34, v34, v35
	v_cvt_pk_bf16_f32 v82, v90, v91
	v_cvt_pk_bf16_f32 v35, v36, v37
	v_cvt_pk_bf16_f32 v83, v92, v93
	v_cvt_pk_bf16_f32 v36, v38, v39
	v_cvt_pk_bf16_f32 v84, v94, v87
	v_cvt_pk_bf16_f32 v37, v40, v41
	v_cvt_pk_bf16_f32 v85, v86, v88
	v_add_f32_e32 v28, v39, v28
	v_add_f32_e32 v221, v90, v221
	v_mfma_f32_32x32x16_bf16 v[66:81], v[138:141], v[34:37], v[66:81]
	v_add_f32_e32 v89, v91, v221
	v_add_f32_e32 v28, v40, v28
	v_mfma_f32_32x32x16_bf16 v[66:81], v[126:129], v[82:85], v[66:81]
	v_exp_f32_e32 v38, v48
	v_add_f32_e32 v89, v92, v89
	v_add_f32_e32 v28, v41, v28
	v_add_f32_e32 v89, v93, v89
	v_mov_b32_e32 v39, v47
	v_add_f32_e32 v89, v94, v89
	v_mfma_f32_32x32x16_bf16 v[50:65], v[122:125], v[34:37], v[50:65]
	v_add_f32_e32 v87, v87, v89
	v_exp_f32_e32 v40, v49
	v_add_f32_e32 v86, v86, v87
	v_cvt_pk_bf16_f32 v34, v42, v43
	v_add_f32_e32 v221, v88, v86
	v_cvt_pk_bf16_f32 v35, v44, v45
	v_mfma_f32_32x32x16_bf16 v[50:65], v[114:117], v[82:85], v[50:65]
	v_cvt_pk_bf16_f32 v36, v46, v39
	v_cvt_pk_bf16_f32 v37, v38, v40
	v_add_f32_e32 v28, v42, v28
	v_add_f32_e32 v41, v43, v28
	v_mfma_f32_32x32x16_bf16 v[66:81], v[110:113], v[34:37], v[66:81]
	v_add_f32_e32 v41, v44, v41
	v_add_f32_e32 v41, v45, v41
	v_add_f32_e32 v41, v46, v41
	v_add_f32_e32 v39, v39, v41
	v_add_f32_e32 v38, v38, v39
	v_add_f32_e32 v28, v40, v38
	v_mfma_f32_32x32x16_bf16 v[50:65], v[106:109], v[34:37], v[50:65]
	v_add_f32_e32 v221, v221, v28
	s_cmp_lg_u32 s85, s86
	s_cbranch_scc1 .Lq_nl1_k0
	s_min_u32 s14, s87, 63
	s_nop 3
	v_readlane_b32 s30, v33, s14
	s_and_b32 s30, s30, 0xff
	s_lshl_b32 s30, s30, 13
	s_or_b32 s30, s30, 0x1000
	s_add_u32 s64, s11, s30
	s_addc_u32 s65, s12, 0
	s_add_u32 s66, s8, s30
	s_addc_u32 s67, s9, 0
	global_load_dwordx4 v[178:181], v2, s[64:65]
	global_load_dwordx4 v[174:177], v2, s[64:65] offset:1024
	global_load_dwordx4 v[170:173], v2, s[64:65] offset:2048
	global_load_dwordx4 v[166:169], v2, s[64:65] offset:3072
	global_load_dwordx4 v[146:149], v2, s[66:67]
	global_load_dwordx4 v[142:145], v2, s[66:67] offset:1024
	global_load_dwordx4 v[126:129], v2, s[66:67] offset:2048
	global_load_dwordx4 v[114:117], v2, s[66:67] offset:3072
	s_min_u32 s14, s88, 63
	s_nop 3
	v_readlane_b32 s30, v33, s14
	s_and_b32 s30, s30, 0xff
	s_lshl_b32 s30, s30, 13
	s_add_u32 s64, s11, s30
	s_addc_u32 s65, s12, 0
	s_add_u32 s66, s8, s30
	s_addc_u32 s67, s9, 0
	global_load_dwordx4 v[162:165], v2, s[64:65]
	global_load_dwordx4 v[154:157], v2, s[64:65] offset:1024
	global_load_dwordx4 v[150:153], v2, s[64:65] offset:2048
	global_load_dwordx4 v[158:161], v2, s[64:65] offset:3072
	global_load_dwordx4 v[138:141], v2, s[66:67]
	global_load_dwordx4 v[122:125], v2, s[66:67] offset:1024
	global_load_dwordx4 v[110:113], v2, s[66:67] offset:2048
	global_load_dwordx4 v[106:109], v2, s[66:67] offset:3072
.Lq_nl1_k0:
	s_mov_b64 s[60:61], 0
	s_lshr_b32 s0, s56, 8
	s_cmp_gt_u32 s0, 0
	s_cbranch_scc0 .Lq_m0_k0
	s_bfe_u32 s1, s57, 0x60000
	s_bitset1_b64 s[60:61], s1
.Lq_m0_k0:
	s_cmp_gt_u32 s0, 1
	s_cbranch_scc0 .Lq_m1_k0
	s_bfe_u32 s1, s57, 0x60006
	s_bitset1_b64 s[60:61], s1
.Lq_m1_k0:
	s_cmp_gt_u32 s0, 2
	s_cbranch_scc0 .Lq_m2_k0
	s_bfe_u32 s1, s57, 0x6000c
	s_bitset1_b64 s[60:61], s1
.Lq_m2_k0:
	s_cmp_gt_u32 s0, 3
	s_cbranch_scc0 .Lq_m3_k0
	s_bfe_u32 s1, s57, 0x60012
	s_bitset1_b64 s[60:61], s1
.Lq_m3_k0:
	s_cmp_gt_u32 s0, 4
	s_cbranch_scc0 .Lq_m4_k0
	s_bfe_u32 s1, s57, 0x60018
	s_bitset1_b64 s[60:61], s1

.Lq_lock_k0:
	s_mov_b64 exec, 1
	v_mov_b32_e32 v16, s60
	v_mov_b32_e32 v17, s61
	ds_or_rtn_b64 v[28:29], v30, v[16:17]
	s_waitcnt lgkmcnt(0)
	v_readfirstlane_b32 s62, v28
	v_readfirstlane_b32 s63, v29
	s_and_b64 s[64:65], s[62:63], s[60:61]
	s_cmp_eq_u64 s[64:65], 0
	s_cbranch_scc1 .Lq_locked_k0
	s_andn2_b64 s[64:65], s[60:61], s[62:63]
	s_not_b64 s[64:65], s[64:65]
	v_mov_b32_e32 v16, s64
	v_mov_b32_e32 v17, s65
	ds_and_b64 v30, v[16:17]
	s_sleep 1
	s_bitcmp1_b32 s77, 0
	s_cbranch_scc0 .Lq_bo0_k0
	s_sleep 1
.Lq_bo0_k0:
	s_bitcmp1_b32 s77, 1
	s_cbranch_scc0 .Lq_bo1_k0
	s_sleep 2
.Lq_bo1_k0:
	s_bitcmp1_b32 s77, 2
	s_cbranch_scc0 .Lq_bo2_k0
	s_sleep 4

.Lq_locked_k0:
	s_mov_b64 exec, s[54:55]
	ds_read_b128 v[82:85], v21
	ds_read_b128 v[86:89], v21 offset:32
	ds_read_b128 v[90:93], v21 offset:64
	ds_read_b128 v[94:97], v21 offset:96
	ds_read_b128 v[34:37], v21 offset:128
	ds_read_b128 v[38:41], v21 offset:160
	ds_read_b128 v[42:45], v21 offset:192
	ds_read_b128 v[46:49], v21 offset:224
	ds_read_b32 v28, v32
	s_waitcnt lgkmcnt(0)
	v_add_f32_e32 v82, v82, v66
	v_add_f32_e32 v83, v83, v67
	v_add_f32_e32 v84, v84, v68
	v_add_f32_e32 v85, v85, v69
	v_add_f32_e32 v86, v86, v70
	v_add_f32_e32 v87, v87, v71
	v_add_f32_e32 v88, v88, v72
	v_add_f32_e32 v89, v89, v73
	v_add_f32_e32 v90, v90, v74
	v_add_f32_e32 v91, v91, v75
	v_add_f32_e32 v92, v92, v76
	v_add_f32_e32 v93, v93, v77
	v_add_f32_e32 v94, v94, v78
	v_add_f32_e32 v95, v95, v79
	v_add_f32_e32 v96, v96, v80
	v_add_f32_e32 v97, v97, v81
	v_add_f32_e32 v34, v34, v50
	v_add_f32_e32 v35, v35, v51
	v_add_f32_e32 v36, v36, v52
	v_add_f32_e32 v37, v37, v53
	v_add_f32_e32 v38, v38, v54
	v_add_f32_e32 v39, v39, v55
	v_add_f32_e32 v40, v40, v56
	v_add_f32_e32 v41, v41, v57
	v_add_f32_e32 v42, v42, v58
	v_add_f32_e32 v43, v43, v59
	v_add_f32_e32 v44, v44, v60
	v_add_f32_e32 v45, v45, v61
	v_add_f32_e32 v46, v46, v62
	v_add_f32_e32 v47, v47, v63
	v_add_f32_e32 v48, v48, v64
	v_add_f32_e32 v49, v49, v65
	v_add_f32_e32 v28, v28, v221
	ds_write_b128 v21, v[82:85]
	ds_write_b128 v21, v[86:89] offset:32
	ds_write_b128 v21, v[90:93] offset:64
	ds_write_b128 v21, v[94:97] offset:96
	ds_write_b128 v21, v[34:37] offset:128
	ds_write_b128 v21, v[38:41] offset:160
	ds_write_b128 v21, v[42:45] offset:192
	ds_write_b128 v21, v[46:49] offset:224
	ds_write_b32 v32, v28
	s_mov_b64 exec, 1
	s_not_b64 s[64:65], s[60:61]
	v_mov_b32_e32 v16, s64
	v_mov_b32_e32 v17, s65
	ds_and_b64 v30, v[16:17]
	s_mov_b64 exec, s[58:59]
	s_mov_b32 s68, s85
	s_cmp_lt_u32 s68, s86
	s_cbranch_scc1 .Lq_tk_k0

.Lq_wd_k1:
	v_mov_b32_e32 v4, v238
	v_mov_b32_e32 v5, v239
	v_mov_b32_e32 v6, v240
	v_mov_b32_e32 v7, v241
	v_mov_b32_e32 v8, v242
	v_mov_b32_e32 v9, v243
	v_mov_b32_e32 v10, v244
	v_mov_b32_e32 v11, v245
	v_mov_b32_e32 v12, v246
	v_mov_b32_e32 v13, v247
	v_mov_b32_e32 v14, v248
	v_mov_b32_e32 v15, v249
	v_mov_b32_e32 v98, v250
	v_mov_b32_e32 v99, v251
	v_mov_b32_e32 v100, v252
	v_mov_b32_e32 v101, v253
	v_bfe_u32 v28, s57, v18, 6
	v_lshl_add_u32 v218, s99, 6, v28
	v_mad_u32_u24 v21, v28, s82, v19
	v_mad_u32_u24 v32, v28, s82, v31
	v_and_b32_e32 v29, s18, v23
	v_cmp_ne_u32_e64 s[54:55], 0, v29
	s_and_b64 s[54:55], s[54:55], s[94:95]
	s_min_u32 s14, s85, 63
	s_nop 3
	v_readlane_b32 s30, v26, s14
	v_readlane_b32 s31, v27, s14
	v_bfe_u32 v28, s31, v18, 6
	v_lshl_add_u32 v29, s99, 6, v28
	v_mad_u32_u24 v29, v29, s47, v20
	global_load_dwordx4 v[238:241], v29, s[20:21]
	global_load_dwordx4 v[242:245], v29, s[20:21] offset:32
	global_load_dwordx4 v[246:249], v29, s[20:21] offset:64
	global_load_dwordx4 v[250:253], v29, s[20:21] offset:96
	s_lshl_b32 s0, s100, 6
	v_or_b32_e32 v237, s0, v206
	v_mov_b32_e32 v221, 0
	s_cmp_lg_u32 s100, s99
	s_cbranch_scc1 .Lq_s0n_k1
	v_and_b32_e32 v82, s18, v23
	v_cmp_ne_u32_e32 vcc, 0, v82
	s_and_b64 vcc, s[94:95], vcc
	v_mov_b32 v83, 0
	v_or_b32_e32 v16, 2, v237
	v_cndmask_b32_e32 v82, v236, v222, vcc
	v_sub_f32_e32 v82, v83, v82
	v_mov_b32_e32 v83, v82
	v_mov_b32_e32 v84, v82
	v_mov_b32_e32 v85, v82
	v_mov_b32_e32 v86, v82
	v_mov_b32_e32 v87, v82
	v_mov_b32_e32 v88, v82
	v_mov_b32_e32 v89, v82
	v_mov_b32_e32 v90, v82
	v_mov_b32_e32 v91, v82
	v_mov_b32_e32 v92, v82
	v_mov_b32_e32 v93, v82
	v_mov_b32_e32 v94, v82
	v_mov_b32_e32 v95, v82
	v_mov_b32_e32 v96, v82
	v_mov_b32_e32 v97, v82
	v_cmp_le_i32_e32 vcc, v237, v218
	v_or_b32_e32 v17, 3, v237
	v_mfma_f32_32x32x16_bf16 v[82:97], v[194:197], v[4:7], v[82:97]
	v_or_b32_e32 v30, 8, v237
	v_mfma_f32_32x32x16_bf16 v[82:97], v[190:193], v[8:11], v[82:97]
	v_mfma_f32_32x32x16_bf16 v[82:97], v[186:189], v[12:15], v[82:97]
	v_mfma_f32_32x32x16_bf16 v[82:97], v[182:185], v[98:101], v[82:97]
	s_nop 11
	v_exp_f32_e32 v82, v82
	v_exp_f32_e32 v83, v83
	v_exp_f32_e32 v84, v84
	v_exp_f32_e32 v85, v85
	v_exp_f32_e32 v86, v86
	v_cndmask_b32_e32 v82, 0, v82, vcc
	v_cmp_lt_i32_e32 vcc, v237, v218
	v_exp_f32_e32 v87, v87
	v_exp_f32_e32 v88, v88
	v_cndmask_b32_e32 v83, 0, v83, vcc
	v_cmp_le_i32_e32 vcc, v16, v218
	v_or_b32_e32 v16, 9, v237
	v_exp_f32_e32 v89, v89
	v_cndmask_b32_e32 v84, 0, v84, vcc
	v_cmp_le_i32_e32 vcc, v17, v218
	v_exp_f32_e32 v90, v90
	v_exp_f32_e32 v91, v91
	v_cndmask_b32_e32 v85, 0, v85, vcc
	v_cmp_le_i32_e32 vcc, v30, v218
	v_add_f32_e32 v221, v221, v82
	v_exp_f32_e32 v92, v92
	v_cndmask_b32_e32 v86, 0, v86, vcc
	v_cmp_le_i32_e32 vcc, v16, v218
	v_or_b32_e32 v16, 10, v237
	v_add_f32_e32 v221, v83, v221
	v_cndmask_b32_e32 v87, 0, v87, vcc
	v_cmp_le_i32_e32 vcc, v16, v218
	v_or_b32_e32 v16, 11, v237
	v_exp_f32_e32 v93, v93
	v_cndmask_b32_e32 v88, 0, v88, vcc
	v_cmp_le_i32_e32 vcc, v16, v218
	v_or_b32_e32 v16, 16, v237
	v_add_f32_e32 v221, v84, v221
	v_cndmask_b32_e32 v89, 0, v89, vcc
	v_cmp_le_i32_e32 vcc, v16, v218
	v_or_b32_e32 v16, 17, v237
	v_exp_f32_e32 v94, v94
	v_cndmask_b32_e32 v90, 0, v90, vcc
	v_cmp_le_i32_e32 vcc, v16, v218
	v_or_b32_e32 v16, 18, v237
	v_add_f32_e32 v221, v85, v221
	v_cndmask_b32_e32 v91, 0, v91, vcc
	v_cmp_le_i32_e32 vcc, v16, v218
	v_or_b32_e32 v16, 19, v237
	v_exp_f32_e32 v95, v95
	v_add_f32_e32 v221, v86, v221
	v_cndmask_b32_e32 v92, 0, v92, vcc
	v_cmp_le_i32_e32 vcc, v16, v218
	v_or_b32_e32 v16, 24, v237
	v_cvt_pk_bf16_f32 v82, v82, v83
	v_cvt_pk_bf16_f32 v83, v84, v85
	v_cvt_pk_bf16_f32 v84, v86, v87
	v_cvt_pk_bf16_f32 v85, v88, v89
	v_add_f32_e32 v221, v87, v221
	v_cndmask_b32_e32 v93, 0, v93, vcc
	v_cmp_le_i32_e32 vcc, v16, v218
	v_or_b32_e32 v16, 25, v237
	v_mfma_f32_32x32x16_bf16 v[66:81], v[134:137], v[82:85], 0
	v_add_f32_e32 v221, v88, v221
	v_cndmask_b32_e32 v94, 0, v94, vcc
	v_exp_f32_e32 v86, v96
	v_cmp_le_i32_e32 vcc, v16, v218
	v_or_b32_e32 v88, 26, v237
	v_add_f32_e32 v221, v89, v221
	v_cndmask_b32_e32 v87, 0, v95, vcc
	v_mfma_f32_32x32x16_bf16 v[50:65], v[130:133], v[82:85], 0
	v_cmp_le_i32_e32 vcc, v88, v218
	v_exp_f32_e32 v88, v97
	v_or_b32_e32 v82, 27, v237
	v_cndmask_b32_e32 v86, 0, v86, vcc
	v_cmp_le_i32_e32 vcc, v82, v218
	v_cvt_pk_bf16_f32 v82, v90, v91
	v_cvt_pk_bf16_f32 v83, v92, v93
	v_cndmask_b32_e32 v88, 0, v88, vcc
	v_cvt_pk_bf16_f32 v84, v94, v87
	v_cvt_pk_bf16_f32 v85, v86, v88
	v_add_f32_e32 v221, v90, v221
	v_add_f32_e32 v89, v91, v221
	v_mfma_f32_32x32x16_bf16 v[66:81], v[118:121], v[82:85], v[66:81]
	v_add_f32_e32 v89, v92, v89
	v_add_f32_e32 v89, v93, v89
	v_add_f32_e32 v89, v94, v89
	v_add_f32_e32 v87, v87, v89
	v_add_f32_e32 v86, v86, v87
	v_add_f32_e32 v221, v88, v86
	v_mfma_f32_32x32x16_bf16 v[50:65], v[102:105], v[82:85], v[50:65]
	s_cmp_lg_u32 s85, s86
	s_cbranch_scc1 .Lq_nl0_k1
	s_min_u32 s14, s87, 63
	s_nop 3
	v_readlane_b32 s30, v33, s14
	s_and_b32 s30, s30, 0xff
	s_lshl_b32 s30, s30, 13
	s_or_b32 s30, s30, 0x1000
	s_add_u32 s64, s11, s30
	s_addc_u32 s65, s12, 0
	s_add_u32 s66, s8, s30
	s_addc_u32 s67, s9, 0
	global_load_dwordx4 v[194:197], v2, s[64:65]
	global_load_dwordx4 v[190:193], v2, s[64:65] offset:1024
	global_load_dwordx4 v[186:189], v2, s[64:65] offset:2048
	global_load_dwordx4 v[182:185], v2, s[64:65] offset:3072
	global_load_dwordx4 v[134:137], v2, s[66:67]
	global_load_dwordx4 v[130:133], v2, s[66:67] offset:1024
	global_load_dwordx4 v[118:121], v2, s[66:67] offset:2048
	global_load_dwordx4 v[102:105], v2, s[66:67] offset:3072
	s_waitcnt vmcnt(20)
	s_branch .Lq_nl0d_k1

.Lq_nl0d_k1:
	s_lshl_b32 s0, s100, 6
	s_or_b32 s0, s0, 32
	v_or_b32_e32 v237, s0, v206
	v_and_b32_e32 v82, s18, v23
	v_cmp_ne_u32_e32 vcc, 0, v82
	s_and_b64 vcc, s[94:95], vcc
	v_mov_b32 v83, 0
	v_or_b32_e32 v16, 2, v237
	v_cndmask_b32_e32 v82, v236, v222, vcc
	v_sub_f32_e32 v82, v83, v82
	v_mov_b32_e32 v83, v82
	v_mov_b32_e32 v84, v82
	v_mov_b32_e32 v85, v82
	v_mov_b32_e32 v86, v82
	v_mov_b32_e32 v87, v82
	v_mov_b32_e32 v88, v82
	v_mov_b32_e32 v89, v82
	v_mov_b32_e32 v90, v82
	v_mov_b32_e32 v91, v82
	v_mov_b32_e32 v92, v82
	v_mov_b32_e32 v93, v82
	v_mov_b32_e32 v94, v82
	v_mov_b32_e32 v95, v82
	v_mov_b32_e32 v96, v82
	v_mov_b32_e32 v97, v82
	v_cmp_le_i32_e32 vcc, v237, v218
	v_or_b32_e32 v17, 3, v237
	v_mfma_f32_32x32x16_bf16 v[82:97], v[178:181], v[4:7], v[82:97]
	v_or_b32_e32 v30, 8, v237
	v_mfma_f32_32x32x16_bf16 v[82:97], v[174:177], v[8:11], v[82:97]
	v_mfma_f32_32x32x16_bf16 v[82:97], v[170:173], v[12:15], v[82:97]
	v_mfma_f32_32x32x16_bf16 v[82:97], v[166:169], v[98:101], v[82:97]
	s_nop 11
	v_exp_f32_e32 v82, v82
	v_exp_f32_e32 v83, v83
	v_exp_f32_e32 v84, v84
	v_exp_f32_e32 v85, v85
	v_exp_f32_e32 v86, v86
	v_cndmask_b32_e32 v82, 0, v82, vcc
	v_cmp_lt_i32_e32 vcc, v237, v218
	v_exp_f32_e32 v87, v87
	v_exp_f32_e32 v88, v88
	v_cndmask_b32_e32 v83, 0, v83, vcc
	v_cmp_le_i32_e32 vcc, v16, v218
	v_or_b32_e32 v16, 9, v237
	v_exp_f32_e32 v89, v89
	v_cndmask_b32_e32 v84, 0, v84, vcc
	v_cmp_le_i32_e32 vcc, v17, v218
	v_exp_f32_e32 v90, v90
	v_exp_f32_e32 v91, v91
	v_cndmask_b32_e32 v85, 0, v85, vcc
	v_cmp_le_i32_e32 vcc, v30, v218
	v_add_f32_e32 v221, v221, v82
	v_exp_f32_e32 v92, v92
	v_cndmask_b32_e32 v86, 0, v86, vcc
	v_cmp_le_i32_e32 vcc, v16, v218
	v_or_b32_e32 v16, 10, v237
	v_add_f32_e32 v221, v83, v221
	v_cndmask_b32_e32 v87, 0, v87, vcc
	v_cmp_le_i32_e32 vcc, v16, v218
	v_or_b32_e32 v16, 11, v237
	v_exp_f32_e32 v93, v93
	v_cndmask_b32_e32 v88, 0, v88, vcc
	v_cmp_le_i32_e32 vcc, v16, v218
	v_or_b32_e32 v16, 16, v237
	v_add_f32_e32 v221, v84, v221
	v_cndmask_b32_e32 v89, 0, v89, vcc
	v_cmp_le_i32_e32 vcc, v16, v218
	v_or_b32_e32 v16, 17, v237
	v_exp_f32_e32 v94, v94
	v_cndmask_b32_e32 v90, 0, v90, vcc
	v_cmp_le_i32_e32 vcc, v16, v218
	v_or_b32_e32 v16, 18, v237
	v_add_f32_e32 v221, v85, v221
	v_cndmask_b32_e32 v91, 0, v91, vcc
	v_cmp_le_i32_e32 vcc, v16, v218
	v_or_b32_e32 v16, 19, v237
	v_exp_f32_e32 v95, v95
	v_add_f32_e32 v221, v86, v221
	v_cndmask_b32_e32 v92, 0, v92, vcc
	v_cmp_le_i32_e32 vcc, v16, v218
	v_or_b32_e32 v16, 24, v237
	v_cvt_pk_bf16_f32 v82, v82, v83
	v_cvt_pk_bf16_f32 v83, v84, v85
	v_cvt_pk_bf16_f32 v84, v86, v87
	v_cvt_pk_bf16_f32 v85, v88, v89
	v_add_f32_e32 v221, v87, v221
	v_cndmask_b32_e32 v93, 0, v93, vcc
	v_cmp_le_i32_e32 vcc, v16, v218
	v_or_b32_e32 v16, 25, v237
	v_mfma_f32_32x32x16_bf16 v[66:81], v[146:149], v[82:85], v[66:81]
	v_add_f32_e32 v221, v88, v221
	v_cndmask_b32_e32 v94, 0, v94, vcc
	v_exp_f32_e32 v86, v96
	v_cmp_le_i32_e32 vcc, v16, v218
	v_or_b32_e32 v88, 26, v237
	v_add_f32_e32 v221, v89, v221
	v_cndmask_b32_e32 v87, 0, v95, vcc
	v_mfma_f32_32x32x16_bf16 v[50:65], v[142:145], v[82:85], v[50:65]
	v_cmp_le_i32_e32 vcc, v88, v218
	v_exp_f32_e32 v88, v97
	v_or_b32_e32 v82, 27, v237
	v_cndmask_b32_e32 v86, 0, v86, vcc
	v_cmp_le_i32_e32 vcc, v82, v218
	v_cvt_pk_bf16_f32 v82, v90, v91
	v_cvt_pk_bf16_f32 v83, v92, v93
	v_cndmask_b32_e32 v88, 0, v88, vcc
	v_cvt_pk_bf16_f32 v84, v94, v87
	v_cvt_pk_bf16_f32 v85, v86, v88
	v_add_f32_e32 v221, v90, v221
	v_add_f32_e32 v89, v91, v221
	v_mfma_f32_32x32x16_bf16 v[66:81], v[126:129], v[82:85], v[66:81]
	v_add_f32_e32 v89, v92, v89
	v_add_f32_e32 v89, v93, v89
	v_add_f32_e32 v89, v94, v89
	v_add_f32_e32 v87, v87, v89
	v_add_f32_e32 v86, v86, v87
	v_add_f32_e32 v221, v88, v86
	v_mfma_f32_32x32x16_bf16 v[50:65], v[114:117], v[82:85], v[50:65]
	s_cmp_lg_u32 s85, s86
	s_cbranch_scc1 .Lq_nl1_k1
	s_min_u32 s14, s88, 63
	s_nop 3
	v_readlane_b32 s30, v33, s14
	s_and_b32 s30, s30, 0xff
	s_lshl_b32 s30, s30, 13
	s_add_u32 s64, s11, s30
	s_addc_u32 s65, s12, 0
	s_add_u32 s66, s8, s30
	s_addc_u32 s67, s9, 0
	global_load_dwordx4 v[178:181], v2, s[64:65]
	global_load_dwordx4 v[174:177], v2, s[64:65] offset:1024
	global_load_dwordx4 v[170:173], v2, s[64:65] offset:2048
	global_load_dwordx4 v[166:169], v2, s[64:65] offset:3072
	global_load_dwordx4 v[146:149], v2, s[66:67]
	global_load_dwordx4 v[142:145], v2, s[66:67] offset:1024
	global_load_dwordx4 v[126:129], v2, s[66:67] offset:2048
	global_load_dwordx4 v[114:117], v2, s[66:67] offset:3072
	s_branch .Lq_nl1_k1
.Lq_s0n_k1:
	v_and_b32_e32 v82, s18, v23
	v_cmp_ne_u32_e32 vcc, 0, v82
	s_and_b64 vcc, s[94:95], vcc
	v_mov_b32 v83, 0
	v_cndmask_b32_e32 v82, v236, v222, vcc
	v_sub_f32_e32 v82, v83, v82
	v_mov_b32_e32 v83, v82
	v_mov_b32_e32 v84, v82
	v_mov_b32_e32 v85, v82
	v_mov_b32_e32 v86, v82
	v_mov_b32_e32 v87, v82
	v_mov_b32_e32 v88, v82
	v_mov_b32_e32 v89, v82
	v_mov_b32_e32 v90, v82
	v_mov_b32_e32 v91, v82
	v_mov_b32_e32 v92, v82
	v_mov_b32_e32 v93, v82
	v_mov_b32_e32 v94, v82
	v_mov_b32_e32 v95, v82
	v_mov_b32_e32 v96, v82
	v_mov_b32_e32 v97, v82
	s_nop 1
	v_mfma_f32_32x32x16_bf16 v[82:97], v[194:197], v[4:7], v[82:97]
	v_mfma_f32_32x32x16_bf16 v[82:97], v[190:193], v[8:11], v[82:97]
	v_mfma_f32_32x32x16_bf16 v[82:97], v[186:189], v[12:15], v[82:97]
	v_mfma_f32_32x32x16_bf16 v[82:97], v[182:185], v[98:101], v[82:97]
	s_waitcnt vmcnt(12)
	v_mov_b32_e32 v28, 0
	v_and_b32_e32 v34, s18, v23
	v_cmp_ne_u32_e32 vcc, 0, v34
	s_and_b64 vcc, s[94:95], vcc
	v_mov_b32 v35, 0
	v_cndmask_b32_e32 v34, v236, v222, vcc
	v_sub_f32_e32 v34, v35, v34
	v_mov_b32_e32 v35, v34
	v_mov_b32_e32 v36, v34
	v_mov_b32_e32 v37, v34
	v_mov_b32_e32 v38, v34
	v_mov_b32_e32 v39, v34
	v_mov_b32_e32 v40, v34
	v_mov_b32_e32 v41, v34
	v_mov_b32_e32 v42, v34
	v_mov_b32_e32 v43, v34
	v_mov_b32_e32 v44, v34
	v_mov_b32_e32 v45, v34
	v_mov_b32_e32 v46, v34
	v_mov_b32_e32 v47, v34
	v_mov_b32_e32 v48, v34
	v_mov_b32_e32 v49, v34
	s_nop 1
	v_mfma_f32_32x32x16_bf16 v[34:49], v[178:181], v[4:7], v[34:49]
	v_mfma_f32_32x32x16_bf16 v[34:49], v[174:177], v[8:11], v[34:49]
	v_mfma_f32_32x32x16_bf16 v[34:49], v[170:173], v[12:15], v[34:49]
	v_mfma_f32_32x32x16_bf16 v[34:49], v[166:169], v[98:101], v[34:49]
	v_exp_f32_e32 v82, v82
	v_exp_f32_e32 v83, v83
	v_exp_f32_e32 v84, v84
	v_exp_f32_e32 v85, v85
	v_exp_f32_e32 v86, v86
	v_exp_f32_e32 v87, v87
	v_exp_f32_e32 v88, v88
	v_exp_f32_e32 v89, v89
	v_exp_f32_e32 v90, v90
	v_exp_f32_e32 v91, v91
	v_add_f32_e32 v221, v221, v82
	v_exp_f32_e32 v92, v92
	v_exp_f32_e32 v34, v34
	v_add_f32_e32 v221, v83, v221
	v_exp_f32_e32 v35, v35
	v_exp_f32_e32 v93, v93
	v_exp_f32_e32 v36, v36
	v_add_f32_e32 v221, v84, v221
	v_exp_f32_e32 v37, v37
	v_exp_f32_e32 v94, v94
	v_exp_f32_e32 v38, v38
	v_add_f32_e32 v221, v85, v221
	v_exp_f32_e32 v39, v39
	v_exp_f32_e32 v95, v95
	v_exp_f32_e32 v40, v40
	v_add_f32_e32 v221, v86, v221
	v_exp_f32_e32 v41, v41
	v_cvt_pk_bf16_f32 v82, v82, v83
	v_exp_f32_e32 v42, v42
	v_cvt_pk_bf16_f32 v83, v84, v85
	v_exp_f32_e32 v43, v43
	v_cvt_pk_bf16_f32 v84, v86, v87
	v_add_f32_e32 v28, v28, v34
	v_cvt_pk_bf16_f32 v85, v88, v89
	v_exp_f32_e32 v44, v44
	v_add_f32_e32 v221, v87, v221
	v_add_f32_e32 v28, v35, v28
	v_mfma_f32_32x32x16_bf16 v[66:81], v[134:137], v[82:85], 0
	v_exp_f32_e32 v45, v45
	v_add_f32_e32 v221, v88, v221
	v_add_f32_e32 v28, v36, v28
	v_exp_f32_e32 v86, v96
	v_exp_f32_e32 v46, v46
	v_add_f32_e32 v221, v89, v221
	v_add_f32_e32 v28, v37, v28
	v_mov_b32_e32 v87, v95
	v_exp_f32_e32 v47, v47
	v_mfma_f32_32x32x16_bf16 v[50:65], v[130:133], v[82:85], 0
	v_add_f32_e32 v28, v38, v28
	v_exp_f32_e32 v88, v97
	v_cvt_pk_bf16_f32 v34, v34, v35
	v_cvt_pk_bf16_f32 v82, v90, v91
	v_cvt_pk_bf16_f32 v35, v36, v37
	v_cvt_pk_bf16_f32 v83, v92, v93
	v_cvt_pk_bf16_f32 v36, v38, v39
	v_cvt_pk_bf16_f32 v84, v94, v87
	v_cvt_pk_bf16_f32 v37, v40, v41
	v_cvt_pk_bf16_f32 v85, v86, v88
	v_add_f32_e32 v28, v39, v28
	v_add_f32_e32 v221, v90, v221
	v_mfma_f32_32x32x16_bf16 v[66:81], v[146:149], v[34:37], v[66:81]
	v_add_f32_e32 v89, v91, v221
	v_add_f32_e32 v28, v40, v28
	v_mfma_f32_32x32x16_bf16 v[66:81], v[118:121], v[82:85], v[66:81]
	v_exp_f32_e32 v38, v48
	v_add_f32_e32 v89, v92, v89
	v_add_f32_e32 v28, v41, v28
	v_add_f32_e32 v89, v93, v89
	v_mov_b32_e32 v39, v47
	v_add_f32_e32 v89, v94, v89
	v_mfma_f32_32x32x16_bf16 v[50:65], v[142:145], v[34:37], v[50:65]
	v_add_f32_e32 v87, v87, v89
	v_exp_f32_e32 v40, v49
	v_add_f32_e32 v86, v86, v87
	v_cvt_pk_bf16_f32 v34, v42, v43
	v_add_f32_e32 v221, v88, v86
	v_cvt_pk_bf16_f32 v35, v44, v45
	v_mfma_f32_32x32x16_bf16 v[50:65], v[102:105], v[82:85], v[50:65]
	v_cvt_pk_bf16_f32 v36, v46, v39
	v_cvt_pk_bf16_f32 v37, v38, v40
	v_add_f32_e32 v28, v42, v28
	v_add_f32_e32 v41, v43, v28
	v_mfma_f32_32x32x16_bf16 v[66:81], v[126:129], v[34:37], v[66:81]
	v_add_f32_e32 v41, v44, v41
	v_add_f32_e32 v41, v45, v41
	v_add_f32_e32 v41, v46, v41
	v_add_f32_e32 v39, v39, v41
	v_add_f32_e32 v38, v38, v39
	v_add_f32_e32 v28, v40, v38
	v_mfma_f32_32x32x16_bf16 v[50:65], v[114:117], v[34:37], v[50:65]
	v_add_f32_e32 v221, v221, v28
	s_cmp_lg_u32 s85, s86
	s_cbranch_scc1 .Lq_nl1_k1
	s_min_u32 s14, s87, 63
	s_nop 3
	v_readlane_b32 s30, v33, s14
	s_and_b32 s30, s30, 0xff
	s_lshl_b32 s30, s30, 13
	s_or_b32 s30, s30, 0x1000
	s_add_u32 s64, s11, s30
	s_addc_u32 s65, s12, 0
	s_add_u32 s66, s8, s30
	s_addc_u32 s67, s9, 0
	global_load_dwordx4 v[194:197], v2, s[64:65]
	global_load_dwordx4 v[190:193], v2, s[64:65] offset:1024
	global_load_dwordx4 v[186:189], v2, s[64:65] offset:2048
	global_load_dwordx4 v[182:185], v2, s[64:65] offset:3072
	global_load_dwordx4 v[134:137], v2, s[66:67]
	global_load_dwordx4 v[130:133], v2, s[66:67] offset:1024
	global_load_dwordx4 v[118:121], v2, s[66:67] offset:2048
	global_load_dwordx4 v[102:105], v2, s[66:67] offset:3072
	s_min_u32 s14, s88, 63
	s_nop 3
	v_readlane_b32 s30, v33, s14
	s_and_b32 s30, s30, 0xff
	s_lshl_b32 s30, s30, 13
	s_add_u32 s64, s11, s30
	s_addc_u32 s65, s12, 0
	s_add_u32 s66, s8, s30
	s_addc_u32 s67, s9, 0
	global_load_dwordx4 v[178:181], v2, s[64:65]
	global_load_dwordx4 v[174:177], v2, s[64:65] offset:1024
	global_load_dwordx4 v[170:173], v2, s[64:65] offset:2048
	global_load_dwordx4 v[166:169], v2, s[64:65] offset:3072
	global_load_dwordx4 v[146:149], v2, s[66:67]
	global_load_dwordx4 v[142:145], v2, s[66:67] offset:1024
	global_load_dwordx4 v[126:129], v2, s[66:67] offset:2048
	global_load_dwordx4 v[114:117], v2, s[66:67] offset:3072

.Lq_wd_k2:
	v_mov_b32_e32 v4, v238
	v_mov_b32_e32 v5, v239
	v_mov_b32_e32 v6, v240
	v_mov_b32_e32 v7, v241
	v_mov_b32_e32 v8, v242
	v_mov_b32_e32 v9, v243
	v_mov_b32_e32 v10, v244
	v_mov_b32_e32 v11, v245
	v_mov_b32_e32 v12, v246
	v_mov_b32_e32 v13, v247
	v_mov_b32_e32 v14, v248
	v_mov_b32_e32 v15, v249
	v_mov_b32_e32 v98, v250
	v_mov_b32_e32 v99, v251
	v_mov_b32_e32 v100, v252
	v_mov_b32_e32 v101, v253
	v_bfe_u32 v28, s57, v18, 6
	v_lshl_add_u32 v218, s99, 6, v28
	v_mad_u32_u24 v21, v28, s82, v19
	v_mad_u32_u24 v32, v28, s82, v31
	v_and_b32_e32 v29, s18, v23
	v_cmp_ne_u32_e64 s[54:55], 0, v29
	s_and_b64 s[54:55], s[54:55], s[94:95]
	s_min_u32 s14, s85, 63
	s_nop 3
	v_readlane_b32 s30, v26, s14
	v_readlane_b32 s31, v27, s14
	v_bfe_u32 v28, s31, v18, 6
	v_lshl_add_u32 v29, s99, 6, v28
	v_mad_u32_u24 v29, v29, s47, v20
	global_load_dwordx4 v[238:241], v29, s[20:21]
	global_load_dwordx4 v[242:245], v29, s[20:21] offset:32
	global_load_dwordx4 v[246:249], v29, s[20:21] offset:64
	global_load_dwordx4 v[250:253], v29, s[20:21] offset:96
	s_lshl_b32 s0, s100, 6
	v_or_b32_e32 v237, s0, v206
	v_mov_b32_e32 v221, 0
	s_cmp_lg_u32 s100, s99
	s_cbranch_scc1 .Lq_s0n_k2
	v_and_b32_e32 v82, s18, v23
	v_cmp_ne_u32_e32 vcc, 0, v82
	s_and_b64 vcc, s[94:95], vcc
	v_mov_b32 v83, 0
	v_or_b32_e32 v16, 2, v237
	v_cndmask_b32_e32 v82, v236, v222, vcc
	v_sub_f32_e32 v82, v83, v82
	v_mov_b32_e32 v83, v82
	v_mov_b32_e32 v84, v82
	v_mov_b32_e32 v85, v82
	v_mov_b32_e32 v86, v82
	v_mov_b32_e32 v87, v82
	v_mov_b32_e32 v88, v82
	v_mov_b32_e32 v89, v82
	v_mov_b32_e32 v90, v82
	v_mov_b32_e32 v91, v82
	v_mov_b32_e32 v92, v82
	v_mov_b32_e32 v93, v82
	v_mov_b32_e32 v94, v82
	v_mov_b32_e32 v95, v82
	v_mov_b32_e32 v96, v82
	v_mov_b32_e32 v97, v82
	v_cmp_le_i32_e32 vcc, v237, v218
	v_or_b32_e32 v17, 3, v237
	v_mfma_f32_32x32x16_bf16 v[82:97], v[162:165], v[4:7], v[82:97]
	v_or_b32_e32 v30, 8, v237
	v_mfma_f32_32x32x16_bf16 v[82:97], v[154:157], v[8:11], v[82:97]
	v_mfma_f32_32x32x16_bf16 v[82:97], v[150:153], v[12:15], v[82:97]
	v_mfma_f32_32x32x16_bf16 v[82:97], v[158:161], v[98:101], v[82:97]
	s_nop 11
	v_exp_f32_e32 v82, v82
	v_exp_f32_e32 v83, v83
	v_exp_f32_e32 v84, v84
	v_exp_f32_e32 v85, v85
	v_exp_f32_e32 v86, v86
	v_cndmask_b32_e32 v82, 0, v82, vcc
	v_cmp_lt_i32_e32 vcc, v237, v218
	v_exp_f32_e32 v87, v87
	v_exp_f32_e32 v88, v88
	v_cndmask_b32_e32 v83, 0, v83, vcc
	v_cmp_le_i32_e32 vcc, v16, v218
	v_or_b32_e32 v16, 9, v237
	v_exp_f32_e32 v89, v89
	v_cndmask_b32_e32 v84, 0, v84, vcc
	v_cmp_le_i32_e32 vcc, v17, v218
	v_exp_f32_e32 v90, v90
	v_exp_f32_e32 v91, v91
	v_cndmask_b32_e32 v85, 0, v85, vcc
	v_cmp_le_i32_e32 vcc, v30, v218
	v_add_f32_e32 v221, v221, v82
	v_exp_f32_e32 v92, v92
	v_cndmask_b32_e32 v86, 0, v86, vcc
	v_cmp_le_i32_e32 vcc, v16, v218
	v_or_b32_e32 v16, 10, v237
	v_add_f32_e32 v221, v83, v221
	v_cndmask_b32_e32 v87, 0, v87, vcc
	v_cmp_le_i32_e32 vcc, v16, v218
	v_or_b32_e32 v16, 11, v237
	v_exp_f32_e32 v93, v93
	v_cndmask_b32_e32 v88, 0, v88, vcc
	v_cmp_le_i32_e32 vcc, v16, v218
	v_or_b32_e32 v16, 16, v237
	v_add_f32_e32 v221, v84, v221
	v_cndmask_b32_e32 v89, 0, v89, vcc
	v_cmp_le_i32_e32 vcc, v16, v218
	v_or_b32_e32 v16, 17, v237
	v_exp_f32_e32 v94, v94
	v_cndmask_b32_e32 v90, 0, v90, vcc
	v_cmp_le_i32_e32 vcc, v16, v218
	v_or_b32_e32 v16, 18, v237
	v_add_f32_e32 v221, v85, v221
	v_cndmask_b32_e32 v91, 0, v91, vcc
	v_cmp_le_i32_e32 vcc, v16, v218
	v_or_b32_e32 v16, 19, v237
	v_exp_f32_e32 v95, v95
	v_add_f32_e32 v221, v86, v221
	v_cndmask_b32_e32 v92, 0, v92, vcc
	v_cmp_le_i32_e32 vcc, v16, v218
	v_or_b32_e32 v16, 24, v237
	v_cvt_pk_bf16_f32 v82, v82, v83
	v_cvt_pk_bf16_f32 v83, v84, v85
	v_cvt_pk_bf16_f32 v84, v86, v87
	v_cvt_pk_bf16_f32 v85, v88, v89
	v_add_f32_e32 v221, v87, v221
	v_cndmask_b32_e32 v93, 0, v93, vcc
	v_cmp_le_i32_e32 vcc, v16, v218
	v_or_b32_e32 v16, 25, v237
	v_mfma_f32_32x32x16_bf16 v[66:81], v[138:141], v[82:85], 0
	v_add_f32_e32 v221, v88, v221
	v_cndmask_b32_e32 v94, 0, v94, vcc
	v_exp_f32_e32 v86, v96
	v_cmp_le_i32_e32 vcc, v16, v218
	v_or_b32_e32 v88, 26, v237
	v_add_f32_e32 v221, v89, v221
	v_cndmask_b32_e32 v87, 0, v95, vcc
	v_mfma_f32_32x32x16_bf16 v[50:65], v[122:125], v[82:85], 0
	v_cmp_le_i32_e32 vcc, v88, v218
	v_exp_f32_e32 v88, v97
	v_or_b32_e32 v82, 27, v237
	v_cndmask_b32_e32 v86, 0, v86, vcc
	v_cmp_le_i32_e32 vcc, v82, v218
	v_cvt_pk_bf16_f32 v82, v90, v91
	v_cvt_pk_bf16_f32 v83, v92, v93
	v_cndmask_b32_e32 v88, 0, v88, vcc
	v_cvt_pk_bf16_f32 v84, v94, v87
	v_cvt_pk_bf16_f32 v85, v86, v88
	v_add_f32_e32 v221, v90, v221
	v_add_f32_e32 v89, v91, v221
	v_mfma_f32_32x32x16_bf16 v[66:81], v[110:113], v[82:85], v[66:81]
	v_add_f32_e32 v89, v92, v89
	v_add_f32_e32 v89, v93, v89
	v_add_f32_e32 v89, v94, v89
	v_add_f32_e32 v87, v87, v89
	v_add_f32_e32 v86, v86, v87
	v_add_f32_e32 v221, v88, v86
	v_mfma_f32_32x32x16_bf16 v[50:65], v[106:109], v[82:85], v[50:65]
	s_cmp_lg_u32 s85, s86
	s_cbranch_scc1 .Lq_nl0_k2
	s_min_u32 s14, s87, 63
	s_nop 3
	v_readlane_b32 s30, v33, s14
	s_and_b32 s30, s30, 0xff
	s_lshl_b32 s30, s30, 13
	s_or_b32 s30, s30, 0x1000
	s_add_u32 s64, s11, s30
	s_addc_u32 s65, s12, 0
	s_add_u32 s66, s8, s30
	s_addc_u32 s67, s9, 0
	global_load_dwordx4 v[162:165], v2, s[64:65]
	global_load_dwordx4 v[154:157], v2, s[64:65] offset:1024
	global_load_dwordx4 v[150:153], v2, s[64:65] offset:2048
	global_load_dwordx4 v[158:161], v2, s[64:65] offset:3072
	global_load_dwordx4 v[138:141], v2, s[66:67]
	global_load_dwordx4 v[122:125], v2, s[66:67] offset:1024
	global_load_dwordx4 v[110:113], v2, s[66:67] offset:2048
	global_load_dwordx4 v[106:109], v2, s[66:67] offset:3072
	s_waitcnt vmcnt(20)
	s_branch .Lq_nl0d_k2

.Lq_nl0d_k2:
	s_lshl_b32 s0, s100, 6
	s_or_b32 s0, s0, 32
	v_or_b32_e32 v237, s0, v206
	v_and_b32_e32 v82, s18, v23
	v_cmp_ne_u32_e32 vcc, 0, v82
	s_and_b64 vcc, s[94:95], vcc
	v_mov_b32 v83, 0
	v_or_b32_e32 v16, 2, v237
	v_cndmask_b32_e32 v82, v236, v222, vcc
	v_sub_f32_e32 v82, v83, v82
	v_mov_b32_e32 v83, v82
	v_mov_b32_e32 v84, v82
	v_mov_b32_e32 v85, v82
	v_mov_b32_e32 v86, v82
	v_mov_b32_e32 v87, v82
	v_mov_b32_e32 v88, v82
	v_mov_b32_e32 v89, v82
	v_mov_b32_e32 v90, v82
	v_mov_b32_e32 v91, v82
	v_mov_b32_e32 v92, v82
	v_mov_b32_e32 v93, v82
	v_mov_b32_e32 v94, v82
	v_mov_b32_e32 v95, v82
	v_mov_b32_e32 v96, v82
	v_mov_b32_e32 v97, v82
	v_cmp_le_i32_e32 vcc, v237, v218
	v_or_b32_e32 v17, 3, v237
	v_mfma_f32_32x32x16_bf16 v[82:97], v[194:197], v[4:7], v[82:97]
	v_or_b32_e32 v30, 8, v237
	v_mfma_f32_32x32x16_bf16 v[82:97], v[190:193], v[8:11], v[82:97]
	v_mfma_f32_32x32x16_bf16 v[82:97], v[186:189], v[12:15], v[82:97]
	v_mfma_f32_32x32x16_bf16 v[82:97], v[182:185], v[98:101], v[82:97]
	s_nop 11
	v_exp_f32_e32 v82, v82
	v_exp_f32_e32 v83, v83
	v_exp_f32_e32 v84, v84
	v_exp_f32_e32 v85, v85
	v_exp_f32_e32 v86, v86
	v_cndmask_b32_e32 v82, 0, v82, vcc
	v_cmp_lt_i32_e32 vcc, v237, v218
	v_exp_f32_e32 v87, v87
	v_exp_f32_e32 v88, v88
	v_cndmask_b32_e32 v83, 0, v83, vcc
	v_cmp_le_i32_e32 vcc, v16, v218
	v_or_b32_e32 v16, 9, v237
	v_exp_f32_e32 v89, v89
	v_cndmask_b32_e32 v84, 0, v84, vcc
	v_cmp_le_i32_e32 vcc, v17, v218
	v_exp_f32_e32 v90, v90
	v_exp_f32_e32 v91, v91
	v_cndmask_b32_e32 v85, 0, v85, vcc
	v_cmp_le_i32_e32 vcc, v30, v218
	v_add_f32_e32 v221, v221, v82
	v_exp_f32_e32 v92, v92
	v_cndmask_b32_e32 v86, 0, v86, vcc
	v_cmp_le_i32_e32 vcc, v16, v218
	v_or_b32_e32 v16, 10, v237
	v_add_f32_e32 v221, v83, v221
	v_cndmask_b32_e32 v87, 0, v87, vcc
	v_cmp_le_i32_e32 vcc, v16, v218
	v_or_b32_e32 v16, 11, v237
	v_exp_f32_e32 v93, v93
	v_cndmask_b32_e32 v88, 0, v88, vcc
	v_cmp_le_i32_e32 vcc, v16, v218
	v_or_b32_e32 v16, 16, v237
	v_add_f32_e32 v221, v84, v221
	v_cndmask_b32_e32 v89, 0, v89, vcc
	v_cmp_le_i32_e32 vcc, v16, v218
	v_or_b32_e32 v16, 17, v237
	v_exp_f32_e32 v94, v94
	v_cndmask_b32_e32 v90, 0, v90, vcc
	v_cmp_le_i32_e32 vcc, v16, v218
	v_or_b32_e32 v16, 18, v237
	v_add_f32_e32 v221, v85, v221
	v_cndmask_b32_e32 v91, 0, v91, vcc
	v_cmp_le_i32_e32 vcc, v16, v218
	v_or_b32_e32 v16, 19, v237
	v_exp_f32_e32 v95, v95
	v_add_f32_e32 v221, v86, v221
	v_cndmask_b32_e32 v92, 0, v92, vcc
	v_cmp_le_i32_e32 vcc, v16, v218
	v_or_b32_e32 v16, 24, v237
	v_cvt_pk_bf16_f32 v82, v82, v83
	v_cvt_pk_bf16_f32 v83, v84, v85
	v_cvt_pk_bf16_f32 v84, v86, v87
	v_cvt_pk_bf16_f32 v85, v88, v89
	v_add_f32_e32 v221, v87, v221
	v_cndmask_b32_e32 v93, 0, v93, vcc
	v_cmp_le_i32_e32 vcc, v16, v218
	v_or_b32_e32 v16, 25, v237
	v_mfma_f32_32x32x16_bf16 v[66:81], v[134:137], v[82:85], v[66:81]
	v_add_f32_e32 v221, v88, v221
	v_cndmask_b32_e32 v94, 0, v94, vcc
	v_exp_f32_e32 v86, v96
	v_cmp_le_i32_e32 vcc, v16, v218
	v_or_b32_e32 v88, 26, v237
	v_add_f32_e32 v221, v89, v221
	v_cndmask_b32_e32 v87, 0, v95, vcc
	v_mfma_f32_32x32x16_bf16 v[50:65], v[130:133], v[82:85], v[50:65]
	v_cmp_le_i32_e32 vcc, v88, v218
	v_exp_f32_e32 v88, v97
	v_or_b32_e32 v82, 27, v237
	v_cndmask_b32_e32 v86, 0, v86, vcc
	v_cmp_le_i32_e32 vcc, v82, v218
	v_cvt_pk_bf16_f32 v82, v90, v91
	v_cvt_pk_bf16_f32 v83, v92, v93
	v_cndmask_b32_e32 v88, 0, v88, vcc
	v_cvt_pk_bf16_f32 v84, v94, v87
	v_cvt_pk_bf16_f32 v85, v86, v88
	v_add_f32_e32 v221, v90, v221
	v_add_f32_e32 v89, v91, v221
	v_mfma_f32_32x32x16_bf16 v[66:81], v[118:121], v[82:85], v[66:81]
	v_add_f32_e32 v89, v92, v89
	v_add_f32_e32 v89, v93, v89
	v_add_f32_e32 v89, v94, v89
	v_add_f32_e32 v87, v87, v89
	v_add_f32_e32 v86, v86, v87
	v_add_f32_e32 v221, v88, v86
	v_mfma_f32_32x32x16_bf16 v[50:65], v[102:105], v[82:85], v[50:65]
	s_cmp_lg_u32 s85, s86
	s_cbranch_scc1 .Lq_nl1_k2
	s_min_u32 s14, s88, 63
	s_nop 3
	v_readlane_b32 s30, v33, s14
	s_and_b32 s30, s30, 0xff
	s_lshl_b32 s30, s30, 13
	s_add_u32 s64, s11, s30
	s_addc_u32 s65, s12, 0
	s_add_u32 s66, s8, s30
	s_addc_u32 s67, s9, 0
	global_load_dwordx4 v[194:197], v2, s[64:65]
	global_load_dwordx4 v[190:193], v2, s[64:65] offset:1024
	global_load_dwordx4 v[186:189], v2, s[64:65] offset:2048
	global_load_dwordx4 v[182:185], v2, s[64:65] offset:3072
	global_load_dwordx4 v[134:137], v2, s[66:67]
	global_load_dwordx4 v[130:133], v2, s[66:67] offset:1024
	global_load_dwordx4 v[118:121], v2, s[66:67] offset:2048
	global_load_dwordx4 v[102:105], v2, s[66:67] offset:3072
	s_branch .Lq_nl1_k2
.Lq_s0n_k2:
	v_and_b32_e32 v82, s18, v23
	v_cmp_ne_u32_e32 vcc, 0, v82
	s_and_b64 vcc, s[94:95], vcc
	v_mov_b32 v83, 0
	v_cndmask_b32_e32 v82, v236, v222, vcc
	v_sub_f32_e32 v82, v83, v82
	v_mov_b32_e32 v83, v82
	v_mov_b32_e32 v84, v82
	v_mov_b32_e32 v85, v82
	v_mov_b32_e32 v86, v82
	v_mov_b32_e32 v87, v82
	v_mov_b32_e32 v88, v82
	v_mov_b32_e32 v89, v82
	v_mov_b32_e32 v90, v82
	v_mov_b32_e32 v91, v82
	v_mov_b32_e32 v92, v82
	v_mov_b32_e32 v93, v82
	v_mov_b32_e32 v94, v82
	v_mov_b32_e32 v95, v82
	v_mov_b32_e32 v96, v82
	v_mov_b32_e32 v97, v82
	s_nop 1
	v_mfma_f32_32x32x16_bf16 v[82:97], v[162:165], v[4:7], v[82:97]
	v_mfma_f32_32x32x16_bf16 v[82:97], v[154:157], v[8:11], v[82:97]
	v_mfma_f32_32x32x16_bf16 v[82:97], v[150:153], v[12:15], v[82:97]
	v_mfma_f32_32x32x16_bf16 v[82:97], v[158:161], v[98:101], v[82:97]
	s_waitcnt vmcnt(12)
	v_mov_b32_e32 v28, 0
	v_and_b32_e32 v34, s18, v23
	v_cmp_ne_u32_e32 vcc, 0, v34
	s_and_b64 vcc, s[94:95], vcc
	v_mov_b32 v35, 0
	v_cndmask_b32_e32 v34, v236, v222, vcc
	v_sub_f32_e32 v34, v35, v34
	v_mov_b32_e32 v35, v34
	v_mov_b32_e32 v36, v34
	v_mov_b32_e32 v37, v34
	v_mov_b32_e32 v38, v34
	v_mov_b32_e32 v39, v34
	v_mov_b32_e32 v40, v34
	v_mov_b32_e32 v41, v34
	v_mov_b32_e32 v42, v34
	v_mov_b32_e32 v43, v34
	v_mov_b32_e32 v44, v34
	v_mov_b32_e32 v45, v34
	v_mov_b32_e32 v46, v34
	v_mov_b32_e32 v47, v34
	v_mov_b32_e32 v48, v34
	v_mov_b32_e32 v49, v34
	s_nop 1
	v_mfma_f32_32x32x16_bf16 v[34:49], v[194:197], v[4:7], v[34:49]
	v_mfma_f32_32x32x16_bf16 v[34:49], v[190:193], v[8:11], v[34:49]
	v_mfma_f32_32x32x16_bf16 v[34:49], v[186:189], v[12:15], v[34:49]
	v_mfma_f32_32x32x16_bf16 v[34:49], v[182:185], v[98:101], v[34:49]
	v_exp_f32_e32 v82, v82
	v_exp_f32_e32 v83, v83
	v_exp_f32_e32 v84, v84
	v_exp_f32_e32 v85, v85
	v_exp_f32_e32 v86, v86
	v_exp_f32_e32 v87, v87
	v_exp_f32_e32 v88, v88
	v_exp_f32_e32 v89, v89
	v_exp_f32_e32 v90, v90
	v_exp_f32_e32 v91, v91
	v_add_f32_e32 v221, v221, v82
	v_exp_f32_e32 v92, v92
	v_exp_f32_e32 v34, v34
	v_add_f32_e32 v221, v83, v221
	v_exp_f32_e32 v35, v35
	v_exp_f32_e32 v93, v93
	v_exp_f32_e32 v36, v36
	v_add_f32_e32 v221, v84, v221
	v_exp_f32_e32 v37, v37
	v_exp_f32_e32 v94, v94
	v_exp_f32_e32 v38, v38
	v_add_f32_e32 v221, v85, v221
	v_exp_f32_e32 v39, v39
	v_exp_f32_e32 v95, v95
	v_exp_f32_e32 v40, v40
	v_add_f32_e32 v221, v86, v221
	v_exp_f32_e32 v41, v41
	v_cvt_pk_bf16_f32 v82, v82, v83
	v_exp_f32_e32 v42, v42
	v_cvt_pk_bf16_f32 v83, v84, v85
	v_exp_f32_e32 v43, v43
	v_cvt_pk_bf16_f32 v84, v86, v87
	v_add_f32_e32 v28, v28, v34
	v_cvt_pk_bf16_f32 v85, v88, v89
	v_exp_f32_e32 v44, v44
	v_add_f32_e32 v221, v87, v221
	v_add_f32_e32 v28, v35, v28
	v_mfma_f32_32x32x16_bf16 v[66:81], v[138:141], v[82:85], 0
	v_exp_f32_e32 v45, v45
	v_add_f32_e32 v221, v88, v221
	v_add_f32_e32 v28, v36, v28
	v_exp_f32_e32 v86, v96
	v_exp_f32_e32 v46, v46
	v_add_f32_e32 v221, v89, v221
	v_add_f32_e32 v28, v37, v28
	v_mov_b32_e32 v87, v95
	v_exp_f32_e32 v47, v47
	v_mfma_f32_32x32x16_bf16 v[50:65], v[122:125], v[82:85], 0
	v_add_f32_e32 v28, v38, v28
	v_exp_f32_e32 v88, v97
	v_cvt_pk_bf16_f32 v34, v34, v35
	v_cvt_pk_bf16_f32 v82, v90, v91
	v_cvt_pk_bf16_f32 v35, v36, v37
	v_cvt_pk_bf16_f32 v83, v92, v93
	v_cvt_pk_bf16_f32 v36, v38, v39
	v_cvt_pk_bf16_f32 v84, v94, v87
	v_cvt_pk_bf16_f32 v37, v40, v41
	v_cvt_pk_bf16_f32 v85, v86, v88
	v_add_f32_e32 v28, v39, v28
	v_add_f32_e32 v221, v90, v221
	v_mfma_f32_32x32x16_bf16 v[66:81], v[134:137], v[34:37], v[66:81]
	v_add_f32_e32 v89, v91, v221
	v_add_f32_e32 v28, v40, v28
	v_mfma_f32_32x32x16_bf16 v[66:81], v[110:113], v[82:85], v[66:81]
	v_exp_f32_e32 v38, v48
	v_add_f32_e32 v89, v92, v89
	v_add_f32_e32 v28, v41, v28
	v_add_f32_e32 v89, v93, v89
	v_mov_b32_e32 v39, v47
	v_add_f32_e32 v89, v94, v89
	v_mfma_f32_32x32x16_bf16 v[50:65], v[130:133], v[34:37], v[50:65]
	v_add_f32_e32 v87, v87, v89
	v_exp_f32_e32 v40, v49
	v_add_f32_e32 v86, v86, v87
	v_cvt_pk_bf16_f32 v34, v42, v43
	v_add_f32_e32 v221, v88, v86
	v_cvt_pk_bf16_f32 v35, v44, v45
	v_mfma_f32_32x32x16_bf16 v[50:65], v[106:109], v[82:85], v[50:65]
	v_cvt_pk_bf16_f32 v36, v46, v39
	v_cvt_pk_bf16_f32 v37, v38, v40
	v_add_f32_e32 v28, v42, v28
	v_add_f32_e32 v41, v43, v28
	v_mfma_f32_32x32x16_bf16 v[66:81], v[118:121], v[34:37], v[66:81]
	v_add_f32_e32 v41, v44, v41
	v_add_f32_e32 v41, v45, v41
	v_add_f32_e32 v41, v46, v41
	v_add_f32_e32 v39, v39, v41
	v_add_f32_e32 v38, v38, v39
	v_add_f32_e32 v28, v40, v38
	v_mfma_f32_32x32x16_bf16 v[50:65], v[102:105], v[34:37], v[50:65]
	v_add_f32_e32 v221, v221, v28
	s_cmp_lg_u32 s85, s86
	s_cbranch_scc1 .Lq_nl1_k2
	s_min_u32 s14, s87, 63
	s_nop 3
	v_readlane_b32 s30, v33, s14
	s_and_b32 s30, s30, 0xff
	s_lshl_b32 s30, s30, 13
	s_or_b32 s30, s30, 0x1000
	s_add_u32 s64, s11, s30
	s_addc_u32 s65, s12, 0
	s_add_u32 s66, s8, s30
	s_addc_u32 s67, s9, 0
	global_load_dwordx4 v[162:165], v2, s[64:65]
	global_load_dwordx4 v[154:157], v2, s[64:65] offset:1024
	global_load_dwordx4 v[150:153], v2, s[64:65] offset:2048
	global_load_dwordx4 v[158:161], v2, s[64:65] offset:3072
	global_load_dwordx4 v[138:141], v2, s[66:67]
	global_load_dwordx4 v[122:125], v2, s[66:67] offset:1024
	global_load_dwordx4 v[110:113], v2, s[66:67] offset:2048
	global_load_dwordx4 v[106:109], v2, s[66:67] offset:3072
	s_min_u32 s14, s88, 63
	s_nop 3
	v_readlane_b32 s30, v33, s14
	s_and_b32 s30, s30, 0xff
	s_lshl_b32 s30, s30, 13
	s_add_u32 s64, s11, s30
	s_addc_u32 s65, s12, 0
	s_add_u32 s66, s8, s30
	s_addc_u32 s67, s9, 0
	global_load_dwordx4 v[194:197], v2, s[64:65]
	global_load_dwordx4 v[190:193], v2, s[64:65] offset:1024
	global_load_dwordx4 v[186:189], v2, s[64:65] offset:2048
	global_load_dwordx4 v[182:185], v2, s[64:65] offset:3072
	global_load_dwordx4 v[134:137], v2, s[66:67]
	global_load_dwordx4 v[130:133], v2, s[66:67] offset:1024
	global_load_dwordx4 v[118:121], v2, s[66:67] offset:2048
	global_load_dwordx4 v[102:105], v2, s[66:67] offset:3072

.Lq_locked_k2:
	s_mov_b64 exec, s[54:55]
	ds_read_b128 v[82:85], v21
	ds_read_b128 v[86:89], v21 offset:32
	ds_read_b128 v[90:93], v21 offset:64
	ds_read_b128 v[94:97], v21 offset:96
	ds_read_b128 v[34:37], v21 offset:128
	ds_read_b128 v[38:41], v21 offset:160
	ds_read_b128 v[42:45], v21 offset:192
	ds_read_b128 v[46:49], v21 offset:224
	ds_read_b32 v28, v32
	s_waitcnt lgkmcnt(0)
	v_add_f32_e32 v82, v82, v66
	v_add_f32_e32 v83, v83, v67
	v_add_f32_e32 v84, v84, v68
	v_add_f32_e32 v85, v85, v69
	v_add_f32_e32 v86, v86, v70
	v_add_f32_e32 v87, v87, v71
	v_add_f32_e32 v88, v88, v72
	v_add_f32_e32 v89, v89, v73
	v_add_f32_e32 v90, v90, v74
	v_add_f32_e32 v91, v91, v75
	v_add_f32_e32 v92, v92, v76
	v_add_f32_e32 v93, v93, v77
	v_add_f32_e32 v94, v94, v78
	v_add_f32_e32 v95, v95, v79
	v_add_f32_e32 v96, v96, v80
	v_add_f32_e32 v97, v97, v81
	v_add_f32_e32 v34, v34, v50
	v_add_f32_e32 v35, v35, v51
	v_add_f32_e32 v36, v36, v52
	v_add_f32_e32 v37, v37, v53
	v_add_f32_e32 v38, v38, v54
	v_add_f32_e32 v39, v39, v55
	v_add_f32_e32 v40, v40, v56
	v_add_f32_e32 v41, v41, v57
	v_add_f32_e32 v42, v42, v58
	v_add_f32_e32 v43, v43, v59
	v_add_f32_e32 v44, v44, v60
	v_add_f32_e32 v45, v45, v61
	v_add_f32_e32 v46, v46, v62
	v_add_f32_e32 v47, v47, v63
	v_add_f32_e32 v48, v48, v64
	v_add_f32_e32 v49, v49, v65
	v_add_f32_e32 v28, v28, v221
	ds_write_b128 v21, v[82:85]
	ds_write_b128 v21, v[86:89] offset:32
	ds_write_b128 v21, v[90:93] offset:64
	ds_write_b128 v21, v[94:97] offset:96
	ds_write_b128 v21, v[34:37] offset:128
	ds_write_b128 v21, v[38:41] offset:160
	ds_write_b128 v21, v[42:45] offset:192
	ds_write_b128 v21, v[46:49] offset:224
	ds_write_b32 v32, v28
	s_mov_b64 exec, 1
	s_not_b64 s[64:65], s[60:61]
	v_mov_b32_e32 v16, s64
	v_mov_b32_e32 v17, s65
	ds_and_b64 v30, v[16:17]
	s_mov_b64 exec, s[58:59]
	s_mov_b32 s68, s85
	s_cmp_lt_u32 s68, s86
	s_cbranch_scc1 .Lq_tk_k2
	s_add_i32 s52, s52, 6
	s_branch .Lq_loop
.Lq_loop_end:
	s_setprio 0
	s_waitcnt vmcnt(0) lgkmcnt(0)
	s_cmp_eq_u32 s83, 0
	s_cbranch_scc1 .Lq_norepeat
	s_add_i32 s83, s83, -1
	s_branch .Lq_again
.Lq_norepeat:
	s_barrier
	v_mov_b32_e32 v82, v22
	v_mad_u32_u24 v86, v226, s82, v19
	v_add_u32_e32 v87, 0x1980, v86
	v_mad_u32_u24 v88, v226, s82, v31
	v_add_u32_e32 v89, 0x1980, v88
	ds_read_b128 v[66:69], v86
	ds_read_b128 v[70:73], v86 offset:32
	ds_read_b128 v[74:77], v86 offset:64
	ds_read_b128 v[78:81], v86 offset:96
	ds_read_b128 v[50:53], v86 offset:128
	ds_read_b128 v[54:57], v86 offset:160
	ds_read_b128 v[58:61], v86 offset:192
	ds_read_b128 v[62:65], v86 offset:224
	ds_read_b32 v221, v88
	ds_read_b128 v[34:37], v87
	ds_read_b128 v[38:41], v87 offset:32
	ds_read_b128 v[42:45], v87 offset:64
	ds_read_b128 v[46:49], v87 offset:96
	ds_read_b128 v[18:21], v87 offset:128
	ds_read_b128 v[22:25], v87 offset:160
	ds_read_b128 v[26:29], v87 offset:192
	ds_read_b128 v[30:33], v87 offset:224
	ds_read_b32 v211, v89
	s_waitcnt lgkmcnt(0)
	v_mov_b32_e32 v218, v82
